# EpiMerge LDS variant with the gate/merged global loads issued before the LDS write phase of each pass
# speedup vs baseline: 1.0099x; 1.0058x over previous
; #define EPI_FOR(u) \
;     _Pragma("unroll") for (int ai = 0; ai < 2; ++ai) _Pragma("unroll") for (int m = 0; m < 4; ++m) _Pragma("unroll") for (int bj = 0; bj < 2; ++bj)
; #define EPI_COL(u) (EPI_CB(u) + 8 * fq)
; DI u32x4 pack8(const float* v) { u32x4 w; w.x = pk2(v[0], v[1]); w.y = pk2(v[2], v[3]); w.z = pk2(v[4], v[5]); w.w = pk2(v[6], v[7]); return w; }
;     DI void operator()(const Acc& acc, const Unit& u, int wr, int wc, int fr, int fq) const {
;         EPI_FOR(u) {
;             const int row = EPI_ROW(u), col = EPI_COL(u); EPI_V(v);
;             const u32x4 gg = *(const u32x4*)(gate + (size_t)row * 3072 + gi * 1024 + col);
;             const float gf[8] = {bflo(gg.x), bfhi(gg.x), bflo(gg.y), bfhi(gg.y), bflo(gg.z), bfhi(gg.z), bflo(gg.w), bfhi(gg.w)};
;             bf16_t* mp = mrg + (size_t)row * 1024 + col;
;             if (accum) {
;                 const u32x4 oo = *(const u32x4*)mp;
;                 const float of[8] = {bflo(oo.x), bfhi(oo.x), bflo(oo.y), bfhi(oo.y), bflo(oo.z), bfhi(oo.z), bflo(oo.w), bfhi(oo.w)};
; #pragma unroll
;                 for (int j = 0; j < 8; ++j) v[j] = of[j] + gf[j] * v[j];
;             } else {
; #pragma unroll
;                 for (int j = 0; j < 8; ++j) v[j] = gf[j] * v[j];
;             }
;             *(u32x4*)mp = pack8(v);
;         }
.LBB0_1061:
	s_lshl_b32 s2, s28, 8
	s_lshl_b32 s6, s29, 8
	v_readfirstlane_b32 s7, v232
	s_lshr_b32 s7, s7, 6
	s_lshl_b32 s7, s7, 4
	v_add_u32_e32 v210, s51, v145
	v_lshlrev_b32_e32 v210, 10, v210
	v_and_b32_e32 v211, 7, v145
	v_lshlrev_b32_e32 v212, 1, v144
	v_xor_b32_e32 v211, v212, v211
	v_lshl_add_u32 v210, v211, 4, v210
	s_lshl_b32 s8, s54, 2
	v_add_u32_e32 v210, s8, v210
	v_xor_b32_e32 v211, 16, v210
	v_lshrrev_b32_e32 v212, 5, v233
	v_and_b32_e32 v213, 31, v233
	v_lshl_add_u32 v214, v213, 3, s6
	v_lshlrev_b32_e32 v214, 1, v214
	v_lshlrev_b32_e32 v213, 1, v213

; #define EPI_FOR(u) \
;     _Pragma("unroll") for (int ai = 0; ai < 2; ++ai) _Pragma("unroll") for (int m = 0; m < 4; ++m) _Pragma("unroll") for (int bj = 0; bj < 2; ++bj)
; #define EPI_COL(u) (EPI_CB(u) + 8 * fq)
; DI u32x4 pack8(const float* v) { u32x4 w; w.x = pk2(v[0], v[1]); w.y = pk2(v[2], v[3]); w.z = pk2(v[4], v[5]); w.w = pk2(v[6], v[7]); return w; }
;     DI void operator()(const Acc& acc, const Unit& u, int wr, int wc, int fr, int fq) const {
;         EPI_FOR(u) {
;             const int row = EPI_ROW(u), col = EPI_COL(u); EPI_V(v);
;             const u32x4 gg = *(const u32x4*)(gate + (size_t)row * 3072 + gi * 1024 + col);
;             const float gf[8] = {bflo(gg.x), bfhi(gg.x), bflo(gg.y), bfhi(gg.y), bflo(gg.z), bfhi(gg.z), bflo(gg.w), bfhi(gg.w)};
;             bf16_t* mp = mrg + (size_t)row * 1024 + col;
;             if (accum) {
;                 const u32x4 oo = *(const u32x4*)mp;
;                 const float of[8] = {bflo(oo.x), bfhi(oo.x), bflo(oo.y), bfhi(oo.y), bflo(oo.z), bfhi(oo.z), bflo(oo.w), bfhi(oo.w)};
; #pragma unroll
;                 for (int j = 0; j < 8; ++j) v[j] = of[j] + gf[j] * v[j];
;             } else {
; #pragma unroll
;                 for (int j = 0; j < 8; ++j) v[j] = gf[j] * v[j];
;             }
;             *(u32x4*)mp = pack8(v);
;         }
	v_add_u32_e32 v215, s7, v212
	s_add_i32 s8, s2, 0
	v_add_u32_e32 v216, s8, v215
	v_mul_u32_u24_e32 v217, 0x1800, v216
	v_add_u32_e32 v217, v217, v214
	v_add_u32_e32 v217, 0x0, v217
	v_lshl_add_u32 v218, v216, 11, v214
	global_load_dwordx4 v[128:131], v217, s[22:23]
	v_add_u32_e32 v219, 0x3000, v217
	global_load_dwordx4 v[132:135], v219, s[22:23]
	v_add_u32_e32 v219, 0x6000, v217
	global_load_dwordx4 v[136:139], v219, s[22:23]
	v_add_u32_e32 v219, 0x9000, v217
	global_load_dwordx4 v[140:143], v219, s[22:23]
	v_add_u32_e32 v219, 0xc000, v217
	global_load_dwordx4 v[144:147], v219, s[22:23]
	v_add_u32_e32 v219, 0xf000, v217
	global_load_dwordx4 v[148:151], v219, s[22:23]
	v_add_u32_e32 v219, 0x12000, v217
	global_load_dwordx4 v[152:155], v219, s[22:23]
	v_add_u32_e32 v219, 0x15000, v217
	global_load_dwordx4 v[156:159], v219, s[22:23]
	s_waitcnt vmcnt(8)
	s_barrier
	ds_write_b128 v210, v[124:127]
	ds_write_b128 v211, v[120:123]
	ds_write_b128 v210, v[116:119] offset:512
	ds_write_b128 v211, v[112:115] offset:512
	ds_write_b128 v210, v[108:111] offset:16384
	ds_write_b128 v211, v[104:107] offset:16384
	ds_write_b128 v210, v[100:103] offset:16896
	ds_write_b128 v211, v[96:99] offset:16896
	ds_write_b128 v210, v[92:95] offset:32768
	ds_write_b128 v211, v[88:91] offset:32768
	ds_write_b128 v210, v[84:87] offset:33280
	ds_write_b128 v211, v[80:83] offset:33280
	ds_write_b128 v210, v[76:79] offset:49152
	ds_write_b128 v211, v[72:75] offset:49152
	ds_write_b128 v210, v[68:71] offset:49664
	ds_write_b128 v211, v[64:67] offset:49664
	s_waitcnt lgkmcnt(0)
	s_barrier
	v_add_u32_e32 v219, 0, v212
	v_and_b32_e32 v219, 7, v219
	v_xor_b32_e32 v219, v213, v219
	v_add_u32_e32 v228, 0, v215
	v_lshlrev_b32_e32 v228, 10, v228
	v_lshl_add_u32 v228, v219, 4, v228
	v_xor_b32_e32 v229, 16, v228
	ds_read_b128 v[244:247], v228
	ds_read_b128 v[220:223], v229
	s_waitcnt vmcnt(7)
	s_waitcnt lgkmcnt(0)
	v_lshlrev_b32_e32 v184, 16, v128
	v_and_b32_e32 v185, 0xffff0000, v128
	v_pk_mul_f32 v[244:245], v[244:245], v[184:185]
	v_lshlrev_b32_e32 v184, 16, v129
	v_and_b32_e32 v185, 0xffff0000, v129
	v_pk_mul_f32 v[246:247], v[246:247], v[184:185]
	v_lshlrev_b32_e32 v184, 16, v130
	v_and_b32_e32 v185, 0xffff0000, v130
	v_pk_mul_f32 v[220:221], v[220:221], v[184:185]
	v_lshlrev_b32_e32 v184, 16, v131
	v_and_b32_e32 v185, 0xffff0000, v131
	v_pk_mul_f32 v[222:223], v[222:223], v[184:185]
	v_cvt_pk_bf16_f32 v128, v244, v245
	v_cvt_pk_bf16_f32 v129, v246, v247
	v_cvt_pk_bf16_f32 v130, v220, v221
	v_cvt_pk_bf16_f32 v131, v222, v223
	global_store_dwordx4 v218, v[128:131], s[24:25]
	v_add_u32_e32 v219, 2, v212
	v_and_b32_e32 v219, 7, v219
	v_xor_b32_e32 v219, v213, v219
	v_add_u32_e32 v228, 2, v215
	v_lshlrev_b32_e32 v228, 10, v228
	v_lshl_add_u32 v228, v219, 4, v228
	v_xor_b32_e32 v229, 16, v228
	ds_read_b128 v[244:247], v228
	ds_read_b128 v[220:223], v229
	s_waitcnt vmcnt(7)
	s_waitcnt lgkmcnt(0)
	v_lshlrev_b32_e32 v184, 16, v132
	v_and_b32_e32 v185, 0xffff0000, v132
	v_pk_mul_f32 v[244:245], v[244:245], v[184:185]
	v_lshlrev_b32_e32 v184, 16, v133
	v_and_b32_e32 v185, 0xffff0000, v133
	v_pk_mul_f32 v[246:247], v[246:247], v[184:185]
	v_lshlrev_b32_e32 v184, 16, v134
	v_and_b32_e32 v185, 0xffff0000, v134
	v_pk_mul_f32 v[220:221], v[220:221], v[184:185]
	v_lshlrev_b32_e32 v184, 16, v135
	v_and_b32_e32 v185, 0xffff0000, v135
	v_pk_mul_f32 v[222:223], v[222:223], v[184:185]
	v_cvt_pk_bf16_f32 v132, v244, v245
	v_cvt_pk_bf16_f32 v133, v246, v247
	v_cvt_pk_bf16_f32 v134, v220, v221
	v_cvt_pk_bf16_f32 v135, v222, v223
	v_add_u32_e32 v219, 0x1000, v218
	global_store_dwordx4 v219, v[132:135], s[24:25]
	v_add_u32_e32 v219, 4, v212
	v_and_b32_e32 v219, 7, v219
	v_xor_b32_e32 v219, v213, v219
	v_add_u32_e32 v228, 4, v215
	v_lshlrev_b32_e32 v228, 10, v228
	v_lshl_add_u32 v228, v219, 4, v228
	v_xor_b32_e32 v229, 16, v228
	ds_read_b128 v[244:247], v228
	ds_read_b128 v[220:223], v229
	s_waitcnt vmcnt(7)
	s_waitcnt lgkmcnt(0)
	v_lshlrev_b32_e32 v184, 16, v136
	v_and_b32_e32 v185, 0xffff0000, v136
	v_pk_mul_f32 v[244:245], v[244:245], v[184:185]
	v_lshlrev_b32_e32 v184, 16, v137
	v_and_b32_e32 v185, 0xffff0000, v137
	v_pk_mul_f32 v[246:247], v[246:247], v[184:185]
	v_lshlrev_b32_e32 v184, 16, v138
	v_and_b32_e32 v185, 0xffff0000, v138
	v_pk_mul_f32 v[220:221], v[220:221], v[184:185]
	v_lshlrev_b32_e32 v184, 16, v139
	v_and_b32_e32 v185, 0xffff0000, v139
	v_pk_mul_f32 v[222:223], v[222:223], v[184:185]
	v_cvt_pk_bf16_f32 v136, v244, v245
	v_cvt_pk_bf16_f32 v137, v246, v247
	v_cvt_pk_bf16_f32 v138, v220, v221
	v_cvt_pk_bf16_f32 v139, v222, v223
	v_add_u32_e32 v219, 0x2000, v218
	global_store_dwordx4 v219, v[136:139], s[24:25]
	v_add_u32_e32 v219, 6, v212
	v_and_b32_e32 v219, 7, v219
	v_xor_b32_e32 v219, v213, v219
	v_add_u32_e32 v228, 6, v215
	v_lshlrev_b32_e32 v228, 10, v228
	v_lshl_add_u32 v228, v219, 4, v228
	v_xor_b32_e32 v229, 16, v228
	ds_read_b128 v[244:247], v228
	ds_read_b128 v[220:223], v229
	s_waitcnt vmcnt(7)
	s_waitcnt lgkmcnt(0)
	v_lshlrev_b32_e32 v184, 16, v140
	v_and_b32_e32 v185, 0xffff0000, v140
	v_pk_mul_f32 v[244:245], v[244:245], v[184:185]
	v_lshlrev_b32_e32 v184, 16, v141
	v_and_b32_e32 v185, 0xffff0000, v141
	v_pk_mul_f32 v[246:247], v[246:247], v[184:185]
	v_lshlrev_b32_e32 v184, 16, v142
	v_and_b32_e32 v185, 0xffff0000, v142
	v_pk_mul_f32 v[220:221], v[220:221], v[184:185]
	v_lshlrev_b32_e32 v184, 16, v143
	v_and_b32_e32 v185, 0xffff0000, v143
	v_pk_mul_f32 v[222:223], v[222:223], v[184:185]
	v_cvt_pk_bf16_f32 v140, v244, v245
	v_cvt_pk_bf16_f32 v141, v246, v247
	v_cvt_pk_bf16_f32 v142, v220, v221
	v_cvt_pk_bf16_f32 v143, v222, v223
	v_add_u32_e32 v219, 0x3000, v218
	global_store_dwordx4 v219, v[140:143], s[24:25]
	v_add_u32_e32 v219, 8, v212
	v_and_b32_e32 v219, 7, v219
	v_xor_b32_e32 v219, v213, v219
	v_add_u32_e32 v228, 8, v215
	v_lshlrev_b32_e32 v228, 10, v228
	v_lshl_add_u32 v228, v219, 4, v228
	v_xor_b32_e32 v229, 16, v228
	ds_read_b128 v[244:247], v228
	ds_read_b128 v[220:223], v229
	s_waitcnt vmcnt(7)
; #define EPI_FOR(u) \
;     _Pragma("unroll") for (int ai = 0; ai < 2; ++ai) _Pragma("unroll") for (int m = 0; m < 4; ++m) _Pragma("unroll") for (int bj = 0; bj < 2; ++bj)
; #define EPI_COL(u) (EPI_CB(u) + 8 * fq)
; DI u32x4 pack8(const float* v) { u32x4 w; w.x = pk2(v[0], v[1]); w.y = pk2(v[2], v[3]); w.z = pk2(v[4], v[5]); w.w = pk2(v[6], v[7]); return w; }
;     DI void operator()(const Acc& acc, const Unit& u, int wr, int wc, int fr, int fq) const {
;         EPI_FOR(u) {
;             const int row = EPI_ROW(u), col = EPI_COL(u); EPI_V(v);
;             const u32x4 gg = *(const u32x4*)(gate + (size_t)row * 3072 + gi * 1024 + col);
;             const float gf[8] = {bflo(gg.x), bfhi(gg.x), bflo(gg.y), bfhi(gg.y), bflo(gg.z), bfhi(gg.z), bflo(gg.w), bfhi(gg.w)};
;             bf16_t* mp = mrg + (size_t)row * 1024 + col;
;             if (accum) {
;                 const u32x4 oo = *(const u32x4*)mp;
;                 const float of[8] = {bflo(oo.x), bfhi(oo.x), bflo(oo.y), bfhi(oo.y), bflo(oo.z), bfhi(oo.z), bflo(oo.w), bfhi(oo.w)};
; #pragma unroll
;                 for (int j = 0; j < 8; ++j) v[j] = of[j] + gf[j] * v[j];
;             } else {
; #pragma unroll
;                 for (int j = 0; j < 8; ++j) v[j] = gf[j] * v[j];
;             }
;             *(u32x4*)mp = pack8(v);
;         }
	s_waitcnt lgkmcnt(0)
	v_lshlrev_b32_e32 v184, 16, v144
	v_and_b32_e32 v185, 0xffff0000, v144
	v_pk_mul_f32 v[244:245], v[244:245], v[184:185]
	v_lshlrev_b32_e32 v184, 16, v145
	v_and_b32_e32 v185, 0xffff0000, v145
	v_pk_mul_f32 v[246:247], v[246:247], v[184:185]
	v_lshlrev_b32_e32 v184, 16, v146
	v_and_b32_e32 v185, 0xffff0000, v146
	v_pk_mul_f32 v[220:221], v[220:221], v[184:185]
	v_lshlrev_b32_e32 v184, 16, v147
	v_and_b32_e32 v185, 0xffff0000, v147
	v_pk_mul_f32 v[222:223], v[222:223], v[184:185]
	v_cvt_pk_bf16_f32 v144, v244, v245
	v_cvt_pk_bf16_f32 v145, v246, v247
	v_cvt_pk_bf16_f32 v146, v220, v221
	v_cvt_pk_bf16_f32 v147, v222, v223
	v_add_u32_e32 v219, 0x4000, v218
	global_store_dwordx4 v219, v[144:147], s[24:25]
	v_add_u32_e32 v219, 10, v212
	v_and_b32_e32 v219, 7, v219
	v_xor_b32_e32 v219, v213, v219
	v_add_u32_e32 v228, 10, v215
	v_lshlrev_b32_e32 v228, 10, v228
	v_lshl_add_u32 v228, v219, 4, v228
	v_xor_b32_e32 v229, 16, v228
	ds_read_b128 v[244:247], v228
	ds_read_b128 v[220:223], v229
	s_waitcnt vmcnt(7)
	s_waitcnt lgkmcnt(0)
	v_lshlrev_b32_e32 v184, 16, v148
	v_and_b32_e32 v185, 0xffff0000, v148
	v_pk_mul_f32 v[244:245], v[244:245], v[184:185]
	v_lshlrev_b32_e32 v184, 16, v149
	v_and_b32_e32 v185, 0xffff0000, v149
	v_pk_mul_f32 v[246:247], v[246:247], v[184:185]
	v_lshlrev_b32_e32 v184, 16, v150
	v_and_b32_e32 v185, 0xffff0000, v150
	v_pk_mul_f32 v[220:221], v[220:221], v[184:185]
	v_lshlrev_b32_e32 v184, 16, v151
	v_and_b32_e32 v185, 0xffff0000, v151
	v_pk_mul_f32 v[222:223], v[222:223], v[184:185]
	v_cvt_pk_bf16_f32 v148, v244, v245
	v_cvt_pk_bf16_f32 v149, v246, v247
	v_cvt_pk_bf16_f32 v150, v220, v221
	v_cvt_pk_bf16_f32 v151, v222, v223
	v_add_u32_e32 v219, 0x5000, v218
	global_store_dwordx4 v219, v[148:151], s[24:25]
	v_add_u32_e32 v219, 12, v212
	v_and_b32_e32 v219, 7, v219
	v_xor_b32_e32 v219, v213, v219
	v_add_u32_e32 v228, 12, v215
	v_lshlrev_b32_e32 v228, 10, v228
	v_lshl_add_u32 v228, v219, 4, v228
	v_xor_b32_e32 v229, 16, v228
	ds_read_b128 v[244:247], v228
	ds_read_b128 v[220:223], v229
	s_waitcnt vmcnt(7)
	s_waitcnt lgkmcnt(0)
	v_lshlrev_b32_e32 v184, 16, v152
	v_and_b32_e32 v185, 0xffff0000, v152
	v_pk_mul_f32 v[244:245], v[244:245], v[184:185]
	v_lshlrev_b32_e32 v184, 16, v153
	v_and_b32_e32 v185, 0xffff0000, v153
	v_pk_mul_f32 v[246:247], v[246:247], v[184:185]
	v_lshlrev_b32_e32 v184, 16, v154
	v_and_b32_e32 v185, 0xffff0000, v154
	v_pk_mul_f32 v[220:221], v[220:221], v[184:185]
	v_lshlrev_b32_e32 v184, 16, v155
	v_and_b32_e32 v185, 0xffff0000, v155
	v_pk_mul_f32 v[222:223], v[222:223], v[184:185]
	v_cvt_pk_bf16_f32 v152, v244, v245
	v_cvt_pk_bf16_f32 v153, v246, v247
	v_cvt_pk_bf16_f32 v154, v220, v221
	v_cvt_pk_bf16_f32 v155, v222, v223
	v_add_u32_e32 v219, 0x6000, v218
	global_store_dwordx4 v219, v[152:155], s[24:25]
	v_add_u32_e32 v219, 14, v212
	v_and_b32_e32 v219, 7, v219
	v_xor_b32_e32 v219, v213, v219
	v_add_u32_e32 v228, 14, v215
	v_lshlrev_b32_e32 v228, 10, v228
	v_lshl_add_u32 v228, v219, 4, v228
	v_xor_b32_e32 v229, 16, v228
	ds_read_b128 v[244:247], v228
	ds_read_b128 v[220:223], v229
	s_waitcnt vmcnt(7)
	s_waitcnt lgkmcnt(0)
	v_lshlrev_b32_e32 v184, 16, v156
	v_and_b32_e32 v185, 0xffff0000, v156
	v_pk_mul_f32 v[244:245], v[244:245], v[184:185]
	v_lshlrev_b32_e32 v184, 16, v157
	v_and_b32_e32 v185, 0xffff0000, v157
	v_pk_mul_f32 v[246:247], v[246:247], v[184:185]
	v_lshlrev_b32_e32 v184, 16, v158
	v_and_b32_e32 v185, 0xffff0000, v158
	v_pk_mul_f32 v[220:221], v[220:221], v[184:185]
	v_lshlrev_b32_e32 v184, 16, v159
	v_and_b32_e32 v185, 0xffff0000, v159
	v_pk_mul_f32 v[222:223], v[222:223], v[184:185]
	v_cvt_pk_bf16_f32 v156, v244, v245
	v_cvt_pk_bf16_f32 v157, v246, v247
	v_cvt_pk_bf16_f32 v158, v220, v221
	v_cvt_pk_bf16_f32 v159, v222, v223
	v_add_u32_e32 v219, 0x7000, v218
	global_store_dwordx4 v219, v[156:159], s[24:25]
	v_add_u32_e32 v215, s7, v212
	s_add_i32 s8, s2, 128
	v_add_u32_e32 v216, s8, v215
	v_mul_u32_u24_e32 v217, 0x1800, v216
	v_add_u32_e32 v217, v217, v214
	v_add_u32_e32 v217, 0x0, v217
	v_lshl_add_u32 v218, v216, 11, v214
	global_load_dwordx4 v[128:131], v217, s[22:23]
	v_add_u32_e32 v219, 0x3000, v217
	global_load_dwordx4 v[132:135], v219, s[22:23]
	v_add_u32_e32 v219, 0x6000, v217
	global_load_dwordx4 v[136:139], v219, s[22:23]
	v_add_u32_e32 v219, 0x9000, v217
	global_load_dwordx4 v[140:143], v219, s[22:23]
	v_add_u32_e32 v219, 0xc000, v217
	global_load_dwordx4 v[144:147], v219, s[22:23]
	v_add_u32_e32 v219, 0xf000, v217
	global_load_dwordx4 v[148:151], v219, s[22:23]
	v_add_u32_e32 v219, 0x12000, v217
	global_load_dwordx4 v[152:155], v219, s[22:23]
	v_add_u32_e32 v219, 0x15000, v217
	global_load_dwordx4 v[156:159], v219, s[22:23]
	s_barrier
	ds_write_b128 v210, v[60:63]
	ds_write_b128 v211, v[56:59]
	ds_write_b128 v210, v[52:55] offset:512
	ds_write_b128 v211, v[48:51] offset:512
	ds_write_b128 v210, v[44:47] offset:16384
	ds_write_b128 v211, v[40:43] offset:16384
	ds_write_b128 v210, v[36:39] offset:16896
	ds_write_b128 v211, v[32:35] offset:16896
	ds_write_b128 v210, v[28:31] offset:32768
	ds_write_b128 v211, v[24:27] offset:32768
	ds_write_b128 v210, v[20:23] offset:33280
	ds_write_b128 v211, v[16:19] offset:33280
	ds_write_b128 v210, v[12:15] offset:49152
	ds_write_b128 v211, v[8:11] offset:49152
	ds_write_b128 v210, v[4:7] offset:49664
	ds_write_b128 v211, v[0:3] offset:49664
	s_waitcnt lgkmcnt(0)
	s_barrier
; #define EPI_FOR(u) \
;     _Pragma("unroll") for (int ai = 0; ai < 2; ++ai) _Pragma("unroll") for (int m = 0; m < 4; ++m) _Pragma("unroll") for (int bj = 0; bj < 2; ++bj)
; #define EPI_COL(u) (EPI_CB(u) + 8 * fq)
; DI u32x4 pack8(const float* v) { u32x4 w; w.x = pk2(v[0], v[1]); w.y = pk2(v[2], v[3]); w.z = pk2(v[4], v[5]); w.w = pk2(v[6], v[7]); return w; }
;     DI void operator()(const Acc& acc, const Unit& u, int wr, int wc, int fr, int fq) const {
;         EPI_FOR(u) {
;             const int row = EPI_ROW(u), col = EPI_COL(u); EPI_V(v);
;             const u32x4 gg = *(const u32x4*)(gate + (size_t)row * 3072 + gi * 1024 + col);
;             const float gf[8] = {bflo(gg.x), bfhi(gg.x), bflo(gg.y), bfhi(gg.y), bflo(gg.z), bfhi(gg.z), bflo(gg.w), bfhi(gg.w)};
;             bf16_t* mp = mrg + (size_t)row * 1024 + col;
;             if (accum) {
;                 const u32x4 oo = *(const u32x4*)mp;
;                 const float of[8] = {bflo(oo.x), bfhi(oo.x), bflo(oo.y), bfhi(oo.y), bflo(oo.z), bfhi(oo.z), bflo(oo.w), bfhi(oo.w)};
; #pragma unroll
;                 for (int j = 0; j < 8; ++j) v[j] = of[j] + gf[j] * v[j];
;             } else {
; #pragma unroll
;                 for (int j = 0; j < 8; ++j) v[j] = gf[j] * v[j];
;             }
;             *(u32x4*)mp = pack8(v);
;         }
	v_add_u32_e32 v219, 0, v212
	v_and_b32_e32 v219, 7, v219
	v_xor_b32_e32 v219, v213, v219
	v_add_u32_e32 v228, 0, v215
	v_lshlrev_b32_e32 v228, 10, v228
	v_lshl_add_u32 v228, v219, 4, v228
	v_xor_b32_e32 v229, 16, v228
	ds_read_b128 v[244:247], v228
	ds_read_b128 v[220:223], v229
	s_waitcnt vmcnt(7)
	s_waitcnt lgkmcnt(0)
	v_lshlrev_b32_e32 v184, 16, v128
	v_and_b32_e32 v185, 0xffff0000, v128
	v_pk_mul_f32 v[244:245], v[244:245], v[184:185]
	v_lshlrev_b32_e32 v184, 16, v129
	v_and_b32_e32 v185, 0xffff0000, v129
	v_pk_mul_f32 v[246:247], v[246:247], v[184:185]
	v_lshlrev_b32_e32 v184, 16, v130
	v_and_b32_e32 v185, 0xffff0000, v130
	v_pk_mul_f32 v[220:221], v[220:221], v[184:185]
	v_lshlrev_b32_e32 v184, 16, v131
	v_and_b32_e32 v185, 0xffff0000, v131
	v_pk_mul_f32 v[222:223], v[222:223], v[184:185]
	v_cvt_pk_bf16_f32 v128, v244, v245
	v_cvt_pk_bf16_f32 v129, v246, v247
	v_cvt_pk_bf16_f32 v130, v220, v221
	v_cvt_pk_bf16_f32 v131, v222, v223
	global_store_dwordx4 v218, v[128:131], s[24:25]
	v_add_u32_e32 v219, 2, v212
	v_and_b32_e32 v219, 7, v219
	v_xor_b32_e32 v219, v213, v219
	v_add_u32_e32 v228, 2, v215
	v_lshlrev_b32_e32 v228, 10, v228
	v_lshl_add_u32 v228, v219, 4, v228
	v_xor_b32_e32 v229, 16, v228
	ds_read_b128 v[244:247], v228
	ds_read_b128 v[220:223], v229
	s_waitcnt vmcnt(7)
	s_waitcnt lgkmcnt(0)
	v_lshlrev_b32_e32 v184, 16, v132
	v_and_b32_e32 v185, 0xffff0000, v132
	v_pk_mul_f32 v[244:245], v[244:245], v[184:185]
	v_lshlrev_b32_e32 v184, 16, v133
	v_and_b32_e32 v185, 0xffff0000, v133
	v_pk_mul_f32 v[246:247], v[246:247], v[184:185]
	v_lshlrev_b32_e32 v184, 16, v134
	v_and_b32_e32 v185, 0xffff0000, v134
	v_pk_mul_f32 v[220:221], v[220:221], v[184:185]
	v_lshlrev_b32_e32 v184, 16, v135
	v_and_b32_e32 v185, 0xffff0000, v135
	v_pk_mul_f32 v[222:223], v[222:223], v[184:185]
	v_cvt_pk_bf16_f32 v132, v244, v245
	v_cvt_pk_bf16_f32 v133, v246, v247
	v_cvt_pk_bf16_f32 v134, v220, v221
	v_cvt_pk_bf16_f32 v135, v222, v223
	v_add_u32_e32 v219, 0x1000, v218
	global_store_dwordx4 v219, v[132:135], s[24:25]
	v_add_u32_e32 v219, 4, v212
	v_and_b32_e32 v219, 7, v219
	v_xor_b32_e32 v219, v213, v219
	v_add_u32_e32 v228, 4, v215
	v_lshlrev_b32_e32 v228, 10, v228
	v_lshl_add_u32 v228, v219, 4, v228
	v_xor_b32_e32 v229, 16, v228
	ds_read_b128 v[244:247], v228
	ds_read_b128 v[220:223], v229
	s_waitcnt vmcnt(7)
	s_waitcnt lgkmcnt(0)
	v_lshlrev_b32_e32 v184, 16, v136
	v_and_b32_e32 v185, 0xffff0000, v136
	v_pk_mul_f32 v[244:245], v[244:245], v[184:185]
	v_lshlrev_b32_e32 v184, 16, v137
	v_and_b32_e32 v185, 0xffff0000, v137
	v_pk_mul_f32 v[246:247], v[246:247], v[184:185]
	v_lshlrev_b32_e32 v184, 16, v138
	v_and_b32_e32 v185, 0xffff0000, v138
	v_pk_mul_f32 v[220:221], v[220:221], v[184:185]
	v_lshlrev_b32_e32 v184, 16, v139
	v_and_b32_e32 v185, 0xffff0000, v139
	v_pk_mul_f32 v[222:223], v[222:223], v[184:185]
	v_cvt_pk_bf16_f32 v136, v244, v245
	v_cvt_pk_bf16_f32 v137, v246, v247
	v_cvt_pk_bf16_f32 v138, v220, v221
	v_cvt_pk_bf16_f32 v139, v222, v223
	v_add_u32_e32 v219, 0x2000, v218
	global_store_dwordx4 v219, v[136:139], s[24:25]
	v_add_u32_e32 v219, 6, v212
	v_and_b32_e32 v219, 7, v219
	v_xor_b32_e32 v219, v213, v219
	v_add_u32_e32 v228, 6, v215
	v_lshlrev_b32_e32 v228, 10, v228
	v_lshl_add_u32 v228, v219, 4, v228
	v_xor_b32_e32 v229, 16, v228
	ds_read_b128 v[244:247], v228
	ds_read_b128 v[220:223], v229
	s_waitcnt vmcnt(7)
	s_waitcnt lgkmcnt(0)
	v_lshlrev_b32_e32 v184, 16, v140
	v_and_b32_e32 v185, 0xffff0000, v140
	v_pk_mul_f32 v[244:245], v[244:245], v[184:185]
	v_lshlrev_b32_e32 v184, 16, v141
	v_and_b32_e32 v185, 0xffff0000, v141
	v_pk_mul_f32 v[246:247], v[246:247], v[184:185]
	v_lshlrev_b32_e32 v184, 16, v142
	v_and_b32_e32 v185, 0xffff0000, v142
	v_pk_mul_f32 v[220:221], v[220:221], v[184:185]
	v_lshlrev_b32_e32 v184, 16, v143
	v_and_b32_e32 v185, 0xffff0000, v143
	v_pk_mul_f32 v[222:223], v[222:223], v[184:185]
	v_cvt_pk_bf16_f32 v140, v244, v245
	v_cvt_pk_bf16_f32 v141, v246, v247
	v_cvt_pk_bf16_f32 v142, v220, v221
	v_cvt_pk_bf16_f32 v143, v222, v223
	v_add_u32_e32 v219, 0x3000, v218
	global_store_dwordx4 v219, v[140:143], s[24:25]
	v_add_u32_e32 v219, 8, v212
	v_and_b32_e32 v219, 7, v219
	v_xor_b32_e32 v219, v213, v219
	v_add_u32_e32 v228, 8, v215
	v_lshlrev_b32_e32 v228, 10, v228
	v_lshl_add_u32 v228, v219, 4, v228
	v_xor_b32_e32 v229, 16, v228
	ds_read_b128 v[244:247], v228
	ds_read_b128 v[220:223], v229
	s_waitcnt vmcnt(7)
; #define PG8_BAR __builtin_amdgcn_s_barrier()
; #define EPI_FOR(u) \
;     _Pragma("unroll") for (int ai = 0; ai < 2; ++ai) _Pragma("unroll") for (int m = 0; m < 4; ++m) _Pragma("unroll") for (int bj = 0; bj < 2; ++bj)
; #define EPI_COL(u) (EPI_CB(u) + 8 * fq)
; DI u32x4 pack8(const float* v) { u32x4 w; w.x = pk2(v[0], v[1]); w.y = pk2(v[2], v[3]); w.z = pk2(v[4], v[5]); w.w = pk2(v[6], v[7]); return w; }
; template <class Epi>
; DI void gemm_phase(LAS unsigned char* lds, const Gemm g, const Sched& S, const Epi& E) {
;     ...
;         if (!has_next) break;
; #pragma unroll
;         for (int a = 0; a < 2; ++a)
; #pragma unroll
;             for (int b = 0; b < 2; ++b)
; #pragma unroll
;                 for (int m = 0; m < 4; ++m)
; #pragma unroll
;                     for (int n = 0; n < 2; ++n) acc[a][b][m][n] = (f32x4){0.f, 0.f, 0.f, 0.f};
;         cur = nxt; cA = nA; cB = nB; ++ui;
;         if (wr == 1) PG8_BAR;
;     DI void operator()(const Acc& acc, const Unit& u, int wr, int wc, int fr, int fq) const {
;         EPI_FOR(u) {
;             const int row = EPI_ROW(u), col = EPI_COL(u); EPI_V(v);
;             const u32x4 gg = *(const u32x4*)(gate + (size_t)row * 3072 + gi * 1024 + col);
;             const float gf[8] = {bflo(gg.x), bfhi(gg.x), bflo(gg.y), bfhi(gg.y), bflo(gg.z), bfhi(gg.z), bflo(gg.w), bfhi(gg.w)};
;             bf16_t* mp = mrg + (size_t)row * 1024 + col;
;             if (accum) {
;                 const u32x4 oo = *(const u32x4*)mp;
;                 const float of[8] = {bflo(oo.x), bfhi(oo.x), bflo(oo.y), bfhi(oo.y), bflo(oo.z), bfhi(oo.z), bflo(oo.w), bfhi(oo.w)};
; #pragma unroll
;                 for (int j = 0; j < 8; ++j) v[j] = of[j] + gf[j] * v[j];
;             } else {
; #pragma unroll
;                 for (int j = 0; j < 8; ++j) v[j] = gf[j] * v[j];
;             }
;             *(u32x4*)mp = pack8(v);
;         }
	s_waitcnt lgkmcnt(0)
	v_lshlrev_b32_e32 v184, 16, v144
	v_and_b32_e32 v185, 0xffff0000, v144
	v_pk_mul_f32 v[244:245], v[244:245], v[184:185]
	v_lshlrev_b32_e32 v184, 16, v145
	v_and_b32_e32 v185, 0xffff0000, v145
	v_pk_mul_f32 v[246:247], v[246:247], v[184:185]
	v_lshlrev_b32_e32 v184, 16, v146
	v_and_b32_e32 v185, 0xffff0000, v146
	v_pk_mul_f32 v[220:221], v[220:221], v[184:185]
	v_lshlrev_b32_e32 v184, 16, v147
	v_and_b32_e32 v185, 0xffff0000, v147
	v_pk_mul_f32 v[222:223], v[222:223], v[184:185]
	v_cvt_pk_bf16_f32 v144, v244, v245
	v_cvt_pk_bf16_f32 v145, v246, v247
	v_cvt_pk_bf16_f32 v146, v220, v221
	v_cvt_pk_bf16_f32 v147, v222, v223
	v_add_u32_e32 v219, 0x4000, v218
	global_store_dwordx4 v219, v[144:147], s[24:25]
	v_add_u32_e32 v219, 10, v212
	v_and_b32_e32 v219, 7, v219
	v_xor_b32_e32 v219, v213, v219
	v_add_u32_e32 v228, 10, v215
	v_lshlrev_b32_e32 v228, 10, v228
	v_lshl_add_u32 v228, v219, 4, v228
	v_xor_b32_e32 v229, 16, v228
	ds_read_b128 v[244:247], v228
	ds_read_b128 v[220:223], v229
	s_waitcnt vmcnt(7)
	s_waitcnt lgkmcnt(0)
	v_lshlrev_b32_e32 v184, 16, v148
	v_and_b32_e32 v185, 0xffff0000, v148
	v_pk_mul_f32 v[244:245], v[244:245], v[184:185]
	v_lshlrev_b32_e32 v184, 16, v149
	v_and_b32_e32 v185, 0xffff0000, v149
	v_pk_mul_f32 v[246:247], v[246:247], v[184:185]
	v_lshlrev_b32_e32 v184, 16, v150
	v_and_b32_e32 v185, 0xffff0000, v150
	v_pk_mul_f32 v[220:221], v[220:221], v[184:185]
	v_lshlrev_b32_e32 v184, 16, v151
	v_and_b32_e32 v185, 0xffff0000, v151
	v_pk_mul_f32 v[222:223], v[222:223], v[184:185]
	v_cvt_pk_bf16_f32 v148, v244, v245
	v_cvt_pk_bf16_f32 v149, v246, v247
	v_cvt_pk_bf16_f32 v150, v220, v221
	v_cvt_pk_bf16_f32 v151, v222, v223
	v_add_u32_e32 v219, 0x5000, v218
	global_store_dwordx4 v219, v[148:151], s[24:25]
	v_add_u32_e32 v219, 12, v212
	v_and_b32_e32 v219, 7, v219
	v_xor_b32_e32 v219, v213, v219
	v_add_u32_e32 v228, 12, v215
	v_lshlrev_b32_e32 v228, 10, v228
	v_lshl_add_u32 v228, v219, 4, v228
	v_xor_b32_e32 v229, 16, v228
	ds_read_b128 v[244:247], v228
	ds_read_b128 v[220:223], v229
	s_waitcnt vmcnt(7)
	s_waitcnt lgkmcnt(0)
	v_lshlrev_b32_e32 v184, 16, v152
	v_and_b32_e32 v185, 0xffff0000, v152
	v_pk_mul_f32 v[244:245], v[244:245], v[184:185]
	v_lshlrev_b32_e32 v184, 16, v153
	v_and_b32_e32 v185, 0xffff0000, v153
	v_pk_mul_f32 v[246:247], v[246:247], v[184:185]
	v_lshlrev_b32_e32 v184, 16, v154
	v_and_b32_e32 v185, 0xffff0000, v154
	v_pk_mul_f32 v[220:221], v[220:221], v[184:185]
	v_lshlrev_b32_e32 v184, 16, v155
	v_and_b32_e32 v185, 0xffff0000, v155
	v_pk_mul_f32 v[222:223], v[222:223], v[184:185]
	v_cvt_pk_bf16_f32 v152, v244, v245
	v_cvt_pk_bf16_f32 v153, v246, v247
	v_cvt_pk_bf16_f32 v154, v220, v221
	v_cvt_pk_bf16_f32 v155, v222, v223
	v_add_u32_e32 v219, 0x6000, v218
	global_store_dwordx4 v219, v[152:155], s[24:25]
	v_add_u32_e32 v219, 14, v212
	v_and_b32_e32 v219, 7, v219
	v_xor_b32_e32 v219, v213, v219
	v_add_u32_e32 v228, 14, v215
	v_lshlrev_b32_e32 v228, 10, v228
	v_lshl_add_u32 v228, v219, 4, v228
	v_xor_b32_e32 v229, 16, v228
	ds_read_b128 v[244:247], v228
	ds_read_b128 v[220:223], v229
	s_waitcnt vmcnt(7)
	s_waitcnt lgkmcnt(0)
	v_lshlrev_b32_e32 v184, 16, v156
	v_and_b32_e32 v185, 0xffff0000, v156
	v_pk_mul_f32 v[244:245], v[244:245], v[184:185]
	v_lshlrev_b32_e32 v184, 16, v157
	v_and_b32_e32 v185, 0xffff0000, v157
	v_pk_mul_f32 v[246:247], v[246:247], v[184:185]
	v_lshlrev_b32_e32 v184, 16, v158
	v_and_b32_e32 v185, 0xffff0000, v158
	v_pk_mul_f32 v[220:221], v[220:221], v[184:185]
	v_lshlrev_b32_e32 v184, 16, v159
	v_and_b32_e32 v185, 0xffff0000, v159
	v_pk_mul_f32 v[222:223], v[222:223], v[184:185]
	v_cvt_pk_bf16_f32 v156, v244, v245
	v_cvt_pk_bf16_f32 v157, v246, v247
	v_cvt_pk_bf16_f32 v158, v220, v221
	v_cvt_pk_bf16_f32 v159, v222, v223
	v_add_u32_e32 v219, 0x7000, v218
	global_store_dwordx4 v219, v[156:159], s[24:25]
	s_mov_b64 s[6:7], -1
	s_and_b64 vcc, exec, s[14:15]
	s_cbranch_vccnz .LBB0_1046
	s_andn2_b64 vcc, exec, s[20:21]
	s_cbranch_vccnz .LBB0_1045
	s_barrier
	s_branch .LBB0_1045

; #define EPI_FOR(u) \
;     _Pragma("unroll") for (int ai = 0; ai < 2; ++ai) _Pragma("unroll") for (int m = 0; m < 4; ++m) _Pragma("unroll") for (int bj = 0; bj < 2; ++bj)
; #define EPI_COL(u) (EPI_CB(u) + 8 * fq)
; DI u32x4 pack8(const float* v) { u32x4 w; w.x = pk2(v[0], v[1]); w.y = pk2(v[2], v[3]); w.z = pk2(v[4], v[5]); w.w = pk2(v[6], v[7]); return w; }
;     DI void operator()(const Acc& acc, const Unit& u, int wr, int wc, int fr, int fq) const {
;         EPI_FOR(u) {
;             const int row = EPI_ROW(u), col = EPI_COL(u); EPI_V(v);
;             const u32x4 gg = *(const u32x4*)(gate + (size_t)row * 3072 + gi * 1024 + col);
;             const float gf[8] = {bflo(gg.x), bfhi(gg.x), bflo(gg.y), bfhi(gg.y), bflo(gg.z), bfhi(gg.z), bflo(gg.w), bfhi(gg.w)};
;             bf16_t* mp = mrg + (size_t)row * 1024 + col;
;             if (accum) {
;                 const u32x4 oo = *(const u32x4*)mp;
;                 const float of[8] = {bflo(oo.x), bfhi(oo.x), bflo(oo.y), bfhi(oo.y), bflo(oo.z), bfhi(oo.z), bflo(oo.w), bfhi(oo.w)};
; #pragma unroll
;                 for (int j = 0; j < 8; ++j) v[j] = of[j] + gf[j] * v[j];
;             } else {
; #pragma unroll
;                 for (int j = 0; j < 8; ++j) v[j] = gf[j] * v[j];
;             }
;             *(u32x4*)mp = pack8(v);
;         }
.LBB0_1222:
	s_lshl_b32 s2, s44, 8
	s_lshl_b32 s6, s28, 8
	v_readfirstlane_b32 s7, v232
	s_lshr_b32 s7, s7, 6
	s_lshl_b32 s7, s7, 4
	v_add_u32_e32 v210, s64, v145
	v_lshlrev_b32_e32 v210, 10, v210
	v_and_b32_e32 v211, 7, v145
	v_lshlrev_b32_e32 v212, 1, v144
	v_xor_b32_e32 v211, v212, v211
	v_lshl_add_u32 v210, v211, 4, v210
	s_lshl_b32 s8, s65, 2
	v_add_u32_e32 v210, s8, v210
	v_xor_b32_e32 v211, 16, v210
	v_lshrrev_b32_e32 v212, 5, v233
	v_and_b32_e32 v213, 31, v233
	v_lshl_add_u32 v214, v213, 3, s6
	v_lshlrev_b32_e32 v214, 1, v214
	v_lshlrev_b32_e32 v213, 1, v213

; #define EPI_FOR(u) \
;     _Pragma("unroll") for (int ai = 0; ai < 2; ++ai) _Pragma("unroll") for (int m = 0; m < 4; ++m) _Pragma("unroll") for (int bj = 0; bj < 2; ++bj)
; #define EPI_COL(u) (EPI_CB(u) + 8 * fq)
; DI u32x4 pack8(const float* v) { u32x4 w; w.x = pk2(v[0], v[1]); w.y = pk2(v[2], v[3]); w.z = pk2(v[4], v[5]); w.w = pk2(v[6], v[7]); return w; }
;     DI void operator()(const Acc& acc, const Unit& u, int wr, int wc, int fr, int fq) const {
;         EPI_FOR(u) {
;             const int row = EPI_ROW(u), col = EPI_COL(u); EPI_V(v);
;             const u32x4 gg = *(const u32x4*)(gate + (size_t)row * 3072 + gi * 1024 + col);
;             const float gf[8] = {bflo(gg.x), bfhi(gg.x), bflo(gg.y), bfhi(gg.y), bflo(gg.z), bfhi(gg.z), bflo(gg.w), bfhi(gg.w)};
;             bf16_t* mp = mrg + (size_t)row * 1024 + col;
;             if (accum) {
;                 const u32x4 oo = *(const u32x4*)mp;
;                 const float of[8] = {bflo(oo.x), bfhi(oo.x), bflo(oo.y), bfhi(oo.y), bflo(oo.z), bfhi(oo.z), bflo(oo.w), bfhi(oo.w)};
; #pragma unroll
;                 for (int j = 0; j < 8; ++j) v[j] = of[j] + gf[j] * v[j];
;             } else {
; #pragma unroll
;                 for (int j = 0; j < 8; ++j) v[j] = gf[j] * v[j];
;             }
;             *(u32x4*)mp = pack8(v);
;         }
	v_add_u32_e32 v215, s7, v212
	s_add_i32 s8, s2, 0
	v_add_u32_e32 v216, s8, v215
	v_mul_u32_u24_e32 v217, 0x1800, v216
	v_add_u32_e32 v217, v217, v214
	v_add_u32_e32 v217, 0x1000, v217
	v_lshl_add_u32 v218, v216, 11, v214
	global_load_dwordx4 v[128:131], v217, s[20:21]
	global_load_dwordx4 v[160:163], v218, s[22:23]
	v_add_u32_e32 v219, 0x3000, v217
	global_load_dwordx4 v[132:135], v219, s[20:21]
	v_add_u32_e32 v219, 0x1000, v218
	global_load_dwordx4 v[164:167], v219, s[22:23]
	v_add_u32_e32 v219, 0x6000, v217
	global_load_dwordx4 v[136:139], v219, s[20:21]
	v_add_u32_e32 v219, 0x2000, v218
	global_load_dwordx4 v[168:171], v219, s[22:23]
	v_add_u32_e32 v219, 0x9000, v217
	global_load_dwordx4 v[140:143], v219, s[20:21]
	v_add_u32_e32 v219, 0x3000, v218
	global_load_dwordx4 v[172:175], v219, s[22:23]
	v_add_u32_e32 v219, 0xc000, v217
	global_load_dwordx4 v[144:147], v219, s[20:21]
	v_add_u32_e32 v219, 0x4000, v218
	global_load_dwordx4 v[176:179], v219, s[22:23]
	v_add_u32_e32 v219, 0xf000, v217
	global_load_dwordx4 v[148:151], v219, s[20:21]
	v_add_u32_e32 v219, 0x5000, v218
	global_load_dwordx4 v[180:183], v219, s[22:23]
	v_add_u32_e32 v219, 0x12000, v217
	global_load_dwordx4 v[152:155], v219, s[20:21]
	v_add_u32_e32 v219, 0x6000, v218
	global_load_dwordx4 v[224:227], v219, s[22:23]
	v_add_u32_e32 v219, 0x15000, v217
	global_load_dwordx4 v[156:159], v219, s[20:21]
	v_add_u32_e32 v219, 0x7000, v218
	global_load_dwordx4 v[240:243], v219, s[22:23]
	s_waitcnt vmcnt(16)
	s_barrier
	ds_write_b128 v210, v[124:127]
	ds_write_b128 v211, v[120:123]
	ds_write_b128 v210, v[116:119] offset:512
	ds_write_b128 v211, v[112:115] offset:512
	ds_write_b128 v210, v[108:111] offset:16384
	ds_write_b128 v211, v[104:107] offset:16384
	ds_write_b128 v210, v[100:103] offset:16896
	ds_write_b128 v211, v[96:99] offset:16896
	ds_write_b128 v210, v[92:95] offset:32768
	ds_write_b128 v211, v[88:91] offset:32768
	ds_write_b128 v210, v[84:87] offset:33280
	ds_write_b128 v211, v[80:83] offset:33280
	ds_write_b128 v210, v[76:79] offset:49152
	ds_write_b128 v211, v[72:75] offset:49152
	ds_write_b128 v210, v[68:71] offset:49664
	ds_write_b128 v211, v[64:67] offset:49664
	s_waitcnt lgkmcnt(0)
	s_barrier
	v_add_u32_e32 v219, 0, v212
	v_and_b32_e32 v219, 7, v219
	v_xor_b32_e32 v219, v213, v219
	v_add_u32_e32 v228, 0, v215
	v_lshlrev_b32_e32 v228, 10, v228
	v_lshl_add_u32 v228, v219, 4, v228
	v_xor_b32_e32 v229, 16, v228
	ds_read_b128 v[244:247], v228
	ds_read_b128 v[220:223], v229
	s_waitcnt vmcnt(14)
	s_waitcnt lgkmcnt(0)
	v_lshlrev_b32_e32 v184, 16, v128
	v_and_b32_e32 v185, 0xffff0000, v128
	v_lshlrev_b32_e32 v186, 16, v160
	v_and_b32_e32 v187, 0xffff0000, v160
	v_pk_fma_f32 v[244:245], v[244:245], v[184:185], v[186:187]
	v_lshlrev_b32_e32 v184, 16, v129
	v_and_b32_e32 v185, 0xffff0000, v129
	v_lshlrev_b32_e32 v186, 16, v161
	v_and_b32_e32 v187, 0xffff0000, v161
	v_pk_fma_f32 v[246:247], v[246:247], v[184:185], v[186:187]
	v_lshlrev_b32_e32 v184, 16, v130
	v_and_b32_e32 v185, 0xffff0000, v130
	v_lshlrev_b32_e32 v186, 16, v162
	v_and_b32_e32 v187, 0xffff0000, v162
	v_pk_fma_f32 v[220:221], v[220:221], v[184:185], v[186:187]
	v_lshlrev_b32_e32 v184, 16, v131
	v_and_b32_e32 v185, 0xffff0000, v131
	v_lshlrev_b32_e32 v186, 16, v163
	v_and_b32_e32 v187, 0xffff0000, v163
	v_pk_fma_f32 v[222:223], v[222:223], v[184:185], v[186:187]
	v_cvt_pk_bf16_f32 v128, v244, v245
	v_cvt_pk_bf16_f32 v129, v246, v247
	v_cvt_pk_bf16_f32 v130, v220, v221
	v_cvt_pk_bf16_f32 v131, v222, v223
	global_store_dwordx4 v218, v[128:131], s[22:23]
	v_add_u32_e32 v219, 2, v212
	v_and_b32_e32 v219, 7, v219
	v_xor_b32_e32 v219, v213, v219
	v_add_u32_e32 v228, 2, v215
	v_lshlrev_b32_e32 v228, 10, v228
	v_lshl_add_u32 v228, v219, 4, v228
	v_xor_b32_e32 v229, 16, v228
	ds_read_b128 v[244:247], v228
	ds_read_b128 v[220:223], v229
	s_waitcnt vmcnt(13)
	s_waitcnt lgkmcnt(0)
	v_lshlrev_b32_e32 v184, 16, v132
	v_and_b32_e32 v185, 0xffff0000, v132
	v_lshlrev_b32_e32 v186, 16, v164
	v_and_b32_e32 v187, 0xffff0000, v164
	v_pk_fma_f32 v[244:245], v[244:245], v[184:185], v[186:187]
	v_lshlrev_b32_e32 v184, 16, v133
	v_and_b32_e32 v185, 0xffff0000, v133
	v_lshlrev_b32_e32 v186, 16, v165
	v_and_b32_e32 v187, 0xffff0000, v165
	v_pk_fma_f32 v[246:247], v[246:247], v[184:185], v[186:187]
	v_lshlrev_b32_e32 v184, 16, v134
	v_and_b32_e32 v185, 0xffff0000, v134
	v_lshlrev_b32_e32 v186, 16, v166
	v_and_b32_e32 v187, 0xffff0000, v166
	v_pk_fma_f32 v[220:221], v[220:221], v[184:185], v[186:187]
	v_lshlrev_b32_e32 v184, 16, v135
	v_and_b32_e32 v185, 0xffff0000, v135
	v_lshlrev_b32_e32 v186, 16, v167
	v_and_b32_e32 v187, 0xffff0000, v167
	v_pk_fma_f32 v[222:223], v[222:223], v[184:185], v[186:187]
	v_cvt_pk_bf16_f32 v132, v244, v245
	v_cvt_pk_bf16_f32 v133, v246, v247
	v_cvt_pk_bf16_f32 v134, v220, v221
	v_cvt_pk_bf16_f32 v135, v222, v223
	v_add_u32_e32 v219, 0x1000, v218
	global_store_dwordx4 v219, v[132:135], s[22:23]
	v_add_u32_e32 v219, 4, v212
	v_and_b32_e32 v219, 7, v219
	v_xor_b32_e32 v219, v213, v219
	v_add_u32_e32 v228, 4, v215
	v_lshlrev_b32_e32 v228, 10, v228
	v_lshl_add_u32 v228, v219, 4, v228
	v_xor_b32_e32 v229, 16, v228
	ds_read_b128 v[244:247], v228
	ds_read_b128 v[220:223], v229
	s_waitcnt vmcnt(12)
	s_waitcnt lgkmcnt(0)
; #define EPI_FOR(u) \
;     _Pragma("unroll") for (int ai = 0; ai < 2; ++ai) _Pragma("unroll") for (int m = 0; m < 4; ++m) _Pragma("unroll") for (int bj = 0; bj < 2; ++bj)
; #define EPI_COL(u) (EPI_CB(u) + 8 * fq)
; DI u32x4 pack8(const float* v) { u32x4 w; w.x = pk2(v[0], v[1]); w.y = pk2(v[2], v[3]); w.z = pk2(v[4], v[5]); w.w = pk2(v[6], v[7]); return w; }
;     DI void operator()(const Acc& acc, const Unit& u, int wr, int wc, int fr, int fq) const {
;         EPI_FOR(u) {
;             const int row = EPI_ROW(u), col = EPI_COL(u); EPI_V(v);
;             const u32x4 gg = *(const u32x4*)(gate + (size_t)row * 3072 + gi * 1024 + col);
;             const float gf[8] = {bflo(gg.x), bfhi(gg.x), bflo(gg.y), bfhi(gg.y), bflo(gg.z), bfhi(gg.z), bflo(gg.w), bfhi(gg.w)};
;             bf16_t* mp = mrg + (size_t)row * 1024 + col;
;             if (accum) {
;                 const u32x4 oo = *(const u32x4*)mp;
;                 const float of[8] = {bflo(oo.x), bfhi(oo.x), bflo(oo.y), bfhi(oo.y), bflo(oo.z), bfhi(oo.z), bflo(oo.w), bfhi(oo.w)};
; #pragma unroll
;                 for (int j = 0; j < 8; ++j) v[j] = of[j] + gf[j] * v[j];
;             } else {
; #pragma unroll
;                 for (int j = 0; j < 8; ++j) v[j] = gf[j] * v[j];
;             }
;             *(u32x4*)mp = pack8(v);
;         }
	v_lshlrev_b32_e32 v184, 16, v136
	v_and_b32_e32 v185, 0xffff0000, v136
	v_lshlrev_b32_e32 v186, 16, v168
	v_and_b32_e32 v187, 0xffff0000, v168
	v_pk_fma_f32 v[244:245], v[244:245], v[184:185], v[186:187]
	v_lshlrev_b32_e32 v184, 16, v137
	v_and_b32_e32 v185, 0xffff0000, v137
	v_lshlrev_b32_e32 v186, 16, v169
	v_and_b32_e32 v187, 0xffff0000, v169
	v_pk_fma_f32 v[246:247], v[246:247], v[184:185], v[186:187]
	v_lshlrev_b32_e32 v184, 16, v138
	v_and_b32_e32 v185, 0xffff0000, v138
	v_lshlrev_b32_e32 v186, 16, v170
	v_and_b32_e32 v187, 0xffff0000, v170
	v_pk_fma_f32 v[220:221], v[220:221], v[184:185], v[186:187]
	v_lshlrev_b32_e32 v184, 16, v139
	v_and_b32_e32 v185, 0xffff0000, v139
	v_lshlrev_b32_e32 v186, 16, v171
	v_and_b32_e32 v187, 0xffff0000, v171
	v_pk_fma_f32 v[222:223], v[222:223], v[184:185], v[186:187]
	v_cvt_pk_bf16_f32 v136, v244, v245
	v_cvt_pk_bf16_f32 v137, v246, v247
	v_cvt_pk_bf16_f32 v138, v220, v221
	v_cvt_pk_bf16_f32 v139, v222, v223
	v_add_u32_e32 v219, 0x2000, v218
	global_store_dwordx4 v219, v[136:139], s[22:23]
	v_add_u32_e32 v219, 6, v212
	v_and_b32_e32 v219, 7, v219
	v_xor_b32_e32 v219, v213, v219
	v_add_u32_e32 v228, 6, v215
	v_lshlrev_b32_e32 v228, 10, v228
	v_lshl_add_u32 v228, v219, 4, v228
	v_xor_b32_e32 v229, 16, v228
	ds_read_b128 v[244:247], v228
	ds_read_b128 v[220:223], v229
	s_waitcnt vmcnt(11)
	s_waitcnt lgkmcnt(0)
	v_lshlrev_b32_e32 v184, 16, v140
	v_and_b32_e32 v185, 0xffff0000, v140
	v_lshlrev_b32_e32 v186, 16, v172
	v_and_b32_e32 v187, 0xffff0000, v172
	v_pk_fma_f32 v[244:245], v[244:245], v[184:185], v[186:187]
	v_lshlrev_b32_e32 v184, 16, v141
	v_and_b32_e32 v185, 0xffff0000, v141
	v_lshlrev_b32_e32 v186, 16, v173
	v_and_b32_e32 v187, 0xffff0000, v173
	v_pk_fma_f32 v[246:247], v[246:247], v[184:185], v[186:187]
	v_lshlrev_b32_e32 v184, 16, v142
	v_and_b32_e32 v185, 0xffff0000, v142
	v_lshlrev_b32_e32 v186, 16, v174
	v_and_b32_e32 v187, 0xffff0000, v174
	v_pk_fma_f32 v[220:221], v[220:221], v[184:185], v[186:187]
	v_lshlrev_b32_e32 v184, 16, v143
	v_and_b32_e32 v185, 0xffff0000, v143
	v_lshlrev_b32_e32 v186, 16, v175
	v_and_b32_e32 v187, 0xffff0000, v175
	v_pk_fma_f32 v[222:223], v[222:223], v[184:185], v[186:187]
	v_cvt_pk_bf16_f32 v140, v244, v245
	v_cvt_pk_bf16_f32 v141, v246, v247
	v_cvt_pk_bf16_f32 v142, v220, v221
	v_cvt_pk_bf16_f32 v143, v222, v223
	v_add_u32_e32 v219, 0x3000, v218
	global_store_dwordx4 v219, v[140:143], s[22:23]
	v_add_u32_e32 v219, 8, v212
	v_and_b32_e32 v219, 7, v219
	v_xor_b32_e32 v219, v213, v219
	v_add_u32_e32 v228, 8, v215
	v_lshlrev_b32_e32 v228, 10, v228
	v_lshl_add_u32 v228, v219, 4, v228
	v_xor_b32_e32 v229, 16, v228
	ds_read_b128 v[244:247], v228
	ds_read_b128 v[220:223], v229
	s_waitcnt vmcnt(10)
	s_waitcnt lgkmcnt(0)
	v_lshlrev_b32_e32 v184, 16, v144
	v_and_b32_e32 v185, 0xffff0000, v144
	v_lshlrev_b32_e32 v186, 16, v176
	v_and_b32_e32 v187, 0xffff0000, v176
	v_pk_fma_f32 v[244:245], v[244:245], v[184:185], v[186:187]
	v_lshlrev_b32_e32 v184, 16, v145
	v_and_b32_e32 v185, 0xffff0000, v145
	v_lshlrev_b32_e32 v186, 16, v177
	v_and_b32_e32 v187, 0xffff0000, v177
	v_pk_fma_f32 v[246:247], v[246:247], v[184:185], v[186:187]
	v_lshlrev_b32_e32 v184, 16, v146
	v_and_b32_e32 v185, 0xffff0000, v146
	v_lshlrev_b32_e32 v186, 16, v178
	v_and_b32_e32 v187, 0xffff0000, v178
	v_pk_fma_f32 v[220:221], v[220:221], v[184:185], v[186:187]
	v_lshlrev_b32_e32 v184, 16, v147
	v_and_b32_e32 v185, 0xffff0000, v147
	v_lshlrev_b32_e32 v186, 16, v179
	v_and_b32_e32 v187, 0xffff0000, v179
	v_pk_fma_f32 v[222:223], v[222:223], v[184:185], v[186:187]
	v_cvt_pk_bf16_f32 v144, v244, v245
	v_cvt_pk_bf16_f32 v145, v246, v247
	v_cvt_pk_bf16_f32 v146, v220, v221
	v_cvt_pk_bf16_f32 v147, v222, v223
	v_add_u32_e32 v219, 0x4000, v218
	global_store_dwordx4 v219, v[144:147], s[22:23]
	v_add_u32_e32 v219, 10, v212
	v_and_b32_e32 v219, 7, v219
	v_xor_b32_e32 v219, v213, v219
	v_add_u32_e32 v228, 10, v215
	v_lshlrev_b32_e32 v228, 10, v228
	v_lshl_add_u32 v228, v219, 4, v228
	v_xor_b32_e32 v229, 16, v228
	ds_read_b128 v[244:247], v228
	ds_read_b128 v[220:223], v229
	s_waitcnt vmcnt(9)
	s_waitcnt lgkmcnt(0)
	v_lshlrev_b32_e32 v184, 16, v148
	v_and_b32_e32 v185, 0xffff0000, v148
	v_lshlrev_b32_e32 v186, 16, v180
	v_and_b32_e32 v187, 0xffff0000, v180
	v_pk_fma_f32 v[244:245], v[244:245], v[184:185], v[186:187]
	v_lshlrev_b32_e32 v184, 16, v149
	v_and_b32_e32 v185, 0xffff0000, v149
	v_lshlrev_b32_e32 v186, 16, v181
	v_and_b32_e32 v187, 0xffff0000, v181
	v_pk_fma_f32 v[246:247], v[246:247], v[184:185], v[186:187]
	v_lshlrev_b32_e32 v184, 16, v150
	v_and_b32_e32 v185, 0xffff0000, v150
	v_lshlrev_b32_e32 v186, 16, v182
	v_and_b32_e32 v187, 0xffff0000, v182
	v_pk_fma_f32 v[220:221], v[220:221], v[184:185], v[186:187]
	v_lshlrev_b32_e32 v184, 16, v151
	v_and_b32_e32 v185, 0xffff0000, v151
	v_lshlrev_b32_e32 v186, 16, v183
	v_and_b32_e32 v187, 0xffff0000, v183
	v_pk_fma_f32 v[222:223], v[222:223], v[184:185], v[186:187]
	v_cvt_pk_bf16_f32 v148, v244, v245
	v_cvt_pk_bf16_f32 v149, v246, v247
	v_cvt_pk_bf16_f32 v150, v220, v221
	v_cvt_pk_bf16_f32 v151, v222, v223
	v_add_u32_e32 v219, 0x5000, v218
	global_store_dwordx4 v219, v[148:151], s[22:23]
	v_add_u32_e32 v219, 12, v212
	v_and_b32_e32 v219, 7, v219
	v_xor_b32_e32 v219, v213, v219
	v_add_u32_e32 v228, 12, v215
	v_lshlrev_b32_e32 v228, 10, v228
	v_lshl_add_u32 v228, v219, 4, v228
	v_xor_b32_e32 v229, 16, v228
	ds_read_b128 v[244:247], v228
	ds_read_b128 v[220:223], v229
	s_waitcnt vmcnt(8)
	s_waitcnt lgkmcnt(0)
; #define EPI_FOR(u) \
;     _Pragma("unroll") for (int ai = 0; ai < 2; ++ai) _Pragma("unroll") for (int m = 0; m < 4; ++m) _Pragma("unroll") for (int bj = 0; bj < 2; ++bj)
; #define EPI_COL(u) (EPI_CB(u) + 8 * fq)
; DI u32x4 pack8(const float* v) { u32x4 w; w.x = pk2(v[0], v[1]); w.y = pk2(v[2], v[3]); w.z = pk2(v[4], v[5]); w.w = pk2(v[6], v[7]); return w; }
;     DI void operator()(const Acc& acc, const Unit& u, int wr, int wc, int fr, int fq) const {
;         EPI_FOR(u) {
;             const int row = EPI_ROW(u), col = EPI_COL(u); EPI_V(v);
;             const u32x4 gg = *(const u32x4*)(gate + (size_t)row * 3072 + gi * 1024 + col);
;             const float gf[8] = {bflo(gg.x), bfhi(gg.x), bflo(gg.y), bfhi(gg.y), bflo(gg.z), bfhi(gg.z), bflo(gg.w), bfhi(gg.w)};
;             bf16_t* mp = mrg + (size_t)row * 1024 + col;
;             if (accum) {
;                 const u32x4 oo = *(const u32x4*)mp;
;                 const float of[8] = {bflo(oo.x), bfhi(oo.x), bflo(oo.y), bfhi(oo.y), bflo(oo.z), bfhi(oo.z), bflo(oo.w), bfhi(oo.w)};
; #pragma unroll
;                 for (int j = 0; j < 8; ++j) v[j] = of[j] + gf[j] * v[j];
;             } else {
; #pragma unroll
;                 for (int j = 0; j < 8; ++j) v[j] = gf[j] * v[j];
;             }
;             *(u32x4*)mp = pack8(v);
;         }
	v_lshlrev_b32_e32 v184, 16, v152
	v_and_b32_e32 v185, 0xffff0000, v152
	v_lshlrev_b32_e32 v186, 16, v224
	v_and_b32_e32 v187, 0xffff0000, v224
	v_pk_fma_f32 v[244:245], v[244:245], v[184:185], v[186:187]
	v_lshlrev_b32_e32 v184, 16, v153
	v_and_b32_e32 v185, 0xffff0000, v153
	v_lshlrev_b32_e32 v186, 16, v225
	v_and_b32_e32 v187, 0xffff0000, v225
	v_pk_fma_f32 v[246:247], v[246:247], v[184:185], v[186:187]
	v_lshlrev_b32_e32 v184, 16, v154
	v_and_b32_e32 v185, 0xffff0000, v154
	v_lshlrev_b32_e32 v186, 16, v226
	v_and_b32_e32 v187, 0xffff0000, v226
	v_pk_fma_f32 v[220:221], v[220:221], v[184:185], v[186:187]
	v_lshlrev_b32_e32 v184, 16, v155
	v_and_b32_e32 v185, 0xffff0000, v155
	v_lshlrev_b32_e32 v186, 16, v227
	v_and_b32_e32 v187, 0xffff0000, v227
	v_pk_fma_f32 v[222:223], v[222:223], v[184:185], v[186:187]
	v_cvt_pk_bf16_f32 v152, v244, v245
	v_cvt_pk_bf16_f32 v153, v246, v247
	v_cvt_pk_bf16_f32 v154, v220, v221
	v_cvt_pk_bf16_f32 v155, v222, v223
	v_add_u32_e32 v219, 0x6000, v218
	global_store_dwordx4 v219, v[152:155], s[22:23]
	v_add_u32_e32 v219, 14, v212
	v_and_b32_e32 v219, 7, v219
	v_xor_b32_e32 v219, v213, v219
	v_add_u32_e32 v228, 14, v215
	v_lshlrev_b32_e32 v228, 10, v228
	v_lshl_add_u32 v228, v219, 4, v228
	v_xor_b32_e32 v229, 16, v228
	ds_read_b128 v[244:247], v228
	ds_read_b128 v[220:223], v229
	s_waitcnt vmcnt(7)
	s_waitcnt lgkmcnt(0)
	v_lshlrev_b32_e32 v184, 16, v156
	v_and_b32_e32 v185, 0xffff0000, v156
	v_lshlrev_b32_e32 v186, 16, v240
	v_and_b32_e32 v187, 0xffff0000, v240
	v_pk_fma_f32 v[244:245], v[244:245], v[184:185], v[186:187]
	v_lshlrev_b32_e32 v184, 16, v157
	v_and_b32_e32 v185, 0xffff0000, v157
	v_lshlrev_b32_e32 v186, 16, v241
	v_and_b32_e32 v187, 0xffff0000, v241
	v_pk_fma_f32 v[246:247], v[246:247], v[184:185], v[186:187]
	v_lshlrev_b32_e32 v184, 16, v158
	v_and_b32_e32 v185, 0xffff0000, v158
	v_lshlrev_b32_e32 v186, 16, v242
	v_and_b32_e32 v187, 0xffff0000, v242
	v_pk_fma_f32 v[220:221], v[220:221], v[184:185], v[186:187]
	v_lshlrev_b32_e32 v184, 16, v159
	v_and_b32_e32 v185, 0xffff0000, v159
	v_lshlrev_b32_e32 v186, 16, v243
	v_and_b32_e32 v187, 0xffff0000, v243
	v_pk_fma_f32 v[222:223], v[222:223], v[184:185], v[186:187]
	v_cvt_pk_bf16_f32 v156, v244, v245
	v_cvt_pk_bf16_f32 v157, v246, v247
	v_cvt_pk_bf16_f32 v158, v220, v221
	v_cvt_pk_bf16_f32 v159, v222, v223
	v_add_u32_e32 v219, 0x7000, v218
	global_store_dwordx4 v219, v[156:159], s[22:23]
	v_add_u32_e32 v215, s7, v212
	s_add_i32 s8, s2, 128
	v_add_u32_e32 v216, s8, v215
	v_mul_u32_u24_e32 v217, 0x1800, v216
	v_add_u32_e32 v217, v217, v214
	v_add_u32_e32 v217, 0x1000, v217
	v_lshl_add_u32 v218, v216, 11, v214
	global_load_dwordx4 v[128:131], v217, s[20:21]
	global_load_dwordx4 v[160:163], v218, s[22:23]
	v_add_u32_e32 v219, 0x3000, v217
	global_load_dwordx4 v[132:135], v219, s[20:21]
	v_add_u32_e32 v219, 0x1000, v218
	global_load_dwordx4 v[164:167], v219, s[22:23]
	v_add_u32_e32 v219, 0x6000, v217
	global_load_dwordx4 v[136:139], v219, s[20:21]
	v_add_u32_e32 v219, 0x2000, v218
	global_load_dwordx4 v[168:171], v219, s[22:23]
	v_add_u32_e32 v219, 0x9000, v217
	global_load_dwordx4 v[140:143], v219, s[20:21]
	v_add_u32_e32 v219, 0x3000, v218
	global_load_dwordx4 v[172:175], v219, s[22:23]
	v_add_u32_e32 v219, 0xc000, v217
	global_load_dwordx4 v[144:147], v219, s[20:21]
	v_add_u32_e32 v219, 0x4000, v218
	global_load_dwordx4 v[176:179], v219, s[22:23]
	v_add_u32_e32 v219, 0xf000, v217
	global_load_dwordx4 v[148:151], v219, s[20:21]
	v_add_u32_e32 v219, 0x5000, v218
	global_load_dwordx4 v[180:183], v219, s[22:23]
	v_add_u32_e32 v219, 0x12000, v217
	global_load_dwordx4 v[152:155], v219, s[20:21]
	v_add_u32_e32 v219, 0x6000, v218
	global_load_dwordx4 v[224:227], v219, s[22:23]
	v_add_u32_e32 v219, 0x15000, v217
	global_load_dwordx4 v[156:159], v219, s[20:21]
	v_add_u32_e32 v219, 0x7000, v218
	global_load_dwordx4 v[240:243], v219, s[22:23]
	s_barrier
	ds_write_b128 v210, v[60:63]
	ds_write_b128 v211, v[56:59]
	ds_write_b128 v210, v[52:55] offset:512
	ds_write_b128 v211, v[48:51] offset:512
	ds_write_b128 v210, v[44:47] offset:16384
	ds_write_b128 v211, v[40:43] offset:16384
	ds_write_b128 v210, v[36:39] offset:16896
	ds_write_b128 v211, v[32:35] offset:16896
	ds_write_b128 v210, v[28:31] offset:32768
	ds_write_b128 v211, v[24:27] offset:32768
	ds_write_b128 v210, v[20:23] offset:33280
	ds_write_b128 v211, v[16:19] offset:33280
	ds_write_b128 v210, v[12:15] offset:49152
	ds_write_b128 v211, v[8:11] offset:49152
	ds_write_b128 v210, v[4:7] offset:49664
	ds_write_b128 v211, v[0:3] offset:49664
	s_waitcnt lgkmcnt(0)
	s_barrier
; #define EPI_FOR(u) \
;     _Pragma("unroll") for (int ai = 0; ai < 2; ++ai) _Pragma("unroll") for (int m = 0; m < 4; ++m) _Pragma("unroll") for (int bj = 0; bj < 2; ++bj)
; #define EPI_COL(u) (EPI_CB(u) + 8 * fq)
; DI u32x4 pack8(const float* v) { u32x4 w; w.x = pk2(v[0], v[1]); w.y = pk2(v[2], v[3]); w.z = pk2(v[4], v[5]); w.w = pk2(v[6], v[7]); return w; }
;     DI void operator()(const Acc& acc, const Unit& u, int wr, int wc, int fr, int fq) const {
;         EPI_FOR(u) {
;             const int row = EPI_ROW(u), col = EPI_COL(u); EPI_V(v);
;             const u32x4 gg = *(const u32x4*)(gate + (size_t)row * 3072 + gi * 1024 + col);
;             const float gf[8] = {bflo(gg.x), bfhi(gg.x), bflo(gg.y), bfhi(gg.y), bflo(gg.z), bfhi(gg.z), bflo(gg.w), bfhi(gg.w)};
;             bf16_t* mp = mrg + (size_t)row * 1024 + col;
;             if (accum) {
;                 const u32x4 oo = *(const u32x4*)mp;
;                 const float of[8] = {bflo(oo.x), bfhi(oo.x), bflo(oo.y), bfhi(oo.y), bflo(oo.z), bfhi(oo.z), bflo(oo.w), bfhi(oo.w)};
; #pragma unroll
;                 for (int j = 0; j < 8; ++j) v[j] = of[j] + gf[j] * v[j];
;             } else {
; #pragma unroll
;                 for (int j = 0; j < 8; ++j) v[j] = gf[j] * v[j];
;             }
;             *(u32x4*)mp = pack8(v);
;         }
	v_add_u32_e32 v219, 0, v212
	v_and_b32_e32 v219, 7, v219
	v_xor_b32_e32 v219, v213, v219
	v_add_u32_e32 v228, 0, v215
	v_lshlrev_b32_e32 v228, 10, v228
	v_lshl_add_u32 v228, v219, 4, v228
	v_xor_b32_e32 v229, 16, v228
	ds_read_b128 v[244:247], v228
	ds_read_b128 v[220:223], v229
	s_waitcnt vmcnt(14)
	s_waitcnt lgkmcnt(0)
	v_lshlrev_b32_e32 v184, 16, v128
	v_and_b32_e32 v185, 0xffff0000, v128
	v_lshlrev_b32_e32 v186, 16, v160
	v_and_b32_e32 v187, 0xffff0000, v160
	v_pk_fma_f32 v[244:245], v[244:245], v[184:185], v[186:187]
	v_lshlrev_b32_e32 v184, 16, v129
	v_and_b32_e32 v185, 0xffff0000, v129
	v_lshlrev_b32_e32 v186, 16, v161
	v_and_b32_e32 v187, 0xffff0000, v161
	v_pk_fma_f32 v[246:247], v[246:247], v[184:185], v[186:187]
	v_lshlrev_b32_e32 v184, 16, v130
	v_and_b32_e32 v185, 0xffff0000, v130
	v_lshlrev_b32_e32 v186, 16, v162
	v_and_b32_e32 v187, 0xffff0000, v162
	v_pk_fma_f32 v[220:221], v[220:221], v[184:185], v[186:187]
	v_lshlrev_b32_e32 v184, 16, v131
	v_and_b32_e32 v185, 0xffff0000, v131
	v_lshlrev_b32_e32 v186, 16, v163
	v_and_b32_e32 v187, 0xffff0000, v163
	v_pk_fma_f32 v[222:223], v[222:223], v[184:185], v[186:187]
	v_cvt_pk_bf16_f32 v128, v244, v245
	v_cvt_pk_bf16_f32 v129, v246, v247
	v_cvt_pk_bf16_f32 v130, v220, v221
	v_cvt_pk_bf16_f32 v131, v222, v223
	global_store_dwordx4 v218, v[128:131], s[22:23]
	v_add_u32_e32 v219, 2, v212
	v_and_b32_e32 v219, 7, v219
	v_xor_b32_e32 v219, v213, v219
	v_add_u32_e32 v228, 2, v215
	v_lshlrev_b32_e32 v228, 10, v228
	v_lshl_add_u32 v228, v219, 4, v228
	v_xor_b32_e32 v229, 16, v228
	ds_read_b128 v[244:247], v228
	ds_read_b128 v[220:223], v229
	s_waitcnt vmcnt(13)
	s_waitcnt lgkmcnt(0)
	v_lshlrev_b32_e32 v184, 16, v132
	v_and_b32_e32 v185, 0xffff0000, v132
	v_lshlrev_b32_e32 v186, 16, v164
	v_and_b32_e32 v187, 0xffff0000, v164
	v_pk_fma_f32 v[244:245], v[244:245], v[184:185], v[186:187]
	v_lshlrev_b32_e32 v184, 16, v133
	v_and_b32_e32 v185, 0xffff0000, v133
	v_lshlrev_b32_e32 v186, 16, v165
	v_and_b32_e32 v187, 0xffff0000, v165
	v_pk_fma_f32 v[246:247], v[246:247], v[184:185], v[186:187]
	v_lshlrev_b32_e32 v184, 16, v134
	v_and_b32_e32 v185, 0xffff0000, v134
	v_lshlrev_b32_e32 v186, 16, v166
	v_and_b32_e32 v187, 0xffff0000, v166
	v_pk_fma_f32 v[220:221], v[220:221], v[184:185], v[186:187]
	v_lshlrev_b32_e32 v184, 16, v135
	v_and_b32_e32 v185, 0xffff0000, v135
	v_lshlrev_b32_e32 v186, 16, v167
	v_and_b32_e32 v187, 0xffff0000, v167
	v_pk_fma_f32 v[222:223], v[222:223], v[184:185], v[186:187]
	v_cvt_pk_bf16_f32 v132, v244, v245
	v_cvt_pk_bf16_f32 v133, v246, v247
	v_cvt_pk_bf16_f32 v134, v220, v221
	v_cvt_pk_bf16_f32 v135, v222, v223
	v_add_u32_e32 v219, 0x1000, v218
	global_store_dwordx4 v219, v[132:135], s[22:23]
	v_add_u32_e32 v219, 4, v212
	v_and_b32_e32 v219, 7, v219
	v_xor_b32_e32 v219, v213, v219
	v_add_u32_e32 v228, 4, v215
	v_lshlrev_b32_e32 v228, 10, v228
	v_lshl_add_u32 v228, v219, 4, v228
	v_xor_b32_e32 v229, 16, v228
	ds_read_b128 v[244:247], v228
	ds_read_b128 v[220:223], v229
	s_waitcnt vmcnt(12)
	s_waitcnt lgkmcnt(0)
	v_lshlrev_b32_e32 v184, 16, v136
	v_and_b32_e32 v185, 0xffff0000, v136
	v_lshlrev_b32_e32 v186, 16, v168
	v_and_b32_e32 v187, 0xffff0000, v168
	v_pk_fma_f32 v[244:245], v[244:245], v[184:185], v[186:187]
	v_lshlrev_b32_e32 v184, 16, v137
	v_and_b32_e32 v185, 0xffff0000, v137
	v_lshlrev_b32_e32 v186, 16, v169
	v_and_b32_e32 v187, 0xffff0000, v169
	v_pk_fma_f32 v[246:247], v[246:247], v[184:185], v[186:187]
	v_lshlrev_b32_e32 v184, 16, v138
	v_and_b32_e32 v185, 0xffff0000, v138
	v_lshlrev_b32_e32 v186, 16, v170
	v_and_b32_e32 v187, 0xffff0000, v170
	v_pk_fma_f32 v[220:221], v[220:221], v[184:185], v[186:187]
	v_lshlrev_b32_e32 v184, 16, v139
	v_and_b32_e32 v185, 0xffff0000, v139
	v_lshlrev_b32_e32 v186, 16, v171
	v_and_b32_e32 v187, 0xffff0000, v171
	v_pk_fma_f32 v[222:223], v[222:223], v[184:185], v[186:187]
	v_cvt_pk_bf16_f32 v136, v244, v245
	v_cvt_pk_bf16_f32 v137, v246, v247
	v_cvt_pk_bf16_f32 v138, v220, v221
	v_cvt_pk_bf16_f32 v139, v222, v223
	v_add_u32_e32 v219, 0x2000, v218
	global_store_dwordx4 v219, v[136:139], s[22:23]
	v_add_u32_e32 v219, 6, v212
	v_and_b32_e32 v219, 7, v219
	v_xor_b32_e32 v219, v213, v219
	v_add_u32_e32 v228, 6, v215
	v_lshlrev_b32_e32 v228, 10, v228
	v_lshl_add_u32 v228, v219, 4, v228
	v_xor_b32_e32 v229, 16, v228
	ds_read_b128 v[244:247], v228
	ds_read_b128 v[220:223], v229
	s_waitcnt vmcnt(11)
	s_waitcnt lgkmcnt(0)
	v_lshlrev_b32_e32 v184, 16, v140
	v_and_b32_e32 v185, 0xffff0000, v140
	v_lshlrev_b32_e32 v186, 16, v172
	v_and_b32_e32 v187, 0xffff0000, v172
	v_pk_fma_f32 v[244:245], v[244:245], v[184:185], v[186:187]
	v_lshlrev_b32_e32 v184, 16, v141
	v_and_b32_e32 v185, 0xffff0000, v141
	v_lshlrev_b32_e32 v186, 16, v173
	v_and_b32_e32 v187, 0xffff0000, v173
	v_pk_fma_f32 v[246:247], v[246:247], v[184:185], v[186:187]
	v_lshlrev_b32_e32 v184, 16, v142
	v_and_b32_e32 v185, 0xffff0000, v142
	v_lshlrev_b32_e32 v186, 16, v174
	v_and_b32_e32 v187, 0xffff0000, v174
	v_pk_fma_f32 v[220:221], v[220:221], v[184:185], v[186:187]
	v_lshlrev_b32_e32 v184, 16, v143
	v_and_b32_e32 v185, 0xffff0000, v143
	v_lshlrev_b32_e32 v186, 16, v175
	v_and_b32_e32 v187, 0xffff0000, v175
	v_pk_fma_f32 v[222:223], v[222:223], v[184:185], v[186:187]
	v_cvt_pk_bf16_f32 v140, v244, v245
	v_cvt_pk_bf16_f32 v141, v246, v247
	v_cvt_pk_bf16_f32 v142, v220, v221
	v_cvt_pk_bf16_f32 v143, v222, v223
	v_add_u32_e32 v219, 0x3000, v218
	global_store_dwordx4 v219, v[140:143], s[22:23]
	v_add_u32_e32 v219, 8, v212
	v_and_b32_e32 v219, 7, v219
	v_xor_b32_e32 v219, v213, v219
	v_add_u32_e32 v228, 8, v215
	v_lshlrev_b32_e32 v228, 10, v228
	v_lshl_add_u32 v228, v219, 4, v228
	v_xor_b32_e32 v229, 16, v228
	ds_read_b128 v[244:247], v228
	ds_read_b128 v[220:223], v229
	s_waitcnt vmcnt(10)
; #define PG8_BAR __builtin_amdgcn_s_barrier()
; #define EPI_FOR(u) \
;     _Pragma("unroll") for (int ai = 0; ai < 2; ++ai) _Pragma("unroll") for (int m = 0; m < 4; ++m) _Pragma("unroll") for (int bj = 0; bj < 2; ++bj)
; #define EPI_COL(u) (EPI_CB(u) + 8 * fq)
; DI u32x4 pack8(const float* v) { u32x4 w; w.x = pk2(v[0], v[1]); w.y = pk2(v[2], v[3]); w.z = pk2(v[4], v[5]); w.w = pk2(v[6], v[7]); return w; }
; template <class Epi>
; DI void gemm_phase(LAS unsigned char* lds, const Gemm g, const Sched& S, const Epi& E) {
;     ...
;         if (!has_next) break;
; #pragma unroll
;         for (int a = 0; a < 2; ++a)
; #pragma unroll
;             for (int b = 0; b < 2; ++b)
; #pragma unroll
;                 for (int m = 0; m < 4; ++m)
; #pragma unroll
;                     for (int n = 0; n < 2; ++n) acc[a][b][m][n] = (f32x4){0.f, 0.f, 0.f, 0.f};
;         cur = nxt; cA = nA; cB = nB; ++ui;
;         if (wr == 1) PG8_BAR;
;     DI void operator()(const Acc& acc, const Unit& u, int wr, int wc, int fr, int fq) const {
;         EPI_FOR(u) {
;             const int row = EPI_ROW(u), col = EPI_COL(u); EPI_V(v);
;             const u32x4 gg = *(const u32x4*)(gate + (size_t)row * 3072 + gi * 1024 + col);
;             const float gf[8] = {bflo(gg.x), bfhi(gg.x), bflo(gg.y), bfhi(gg.y), bflo(gg.z), bfhi(gg.z), bflo(gg.w), bfhi(gg.w)};
;             bf16_t* mp = mrg + (size_t)row * 1024 + col;
;             if (accum) {
;                 const u32x4 oo = *(const u32x4*)mp;
;                 const float of[8] = {bflo(oo.x), bfhi(oo.x), bflo(oo.y), bfhi(oo.y), bflo(oo.z), bfhi(oo.z), bflo(oo.w), bfhi(oo.w)};
; #pragma unroll
;                 for (int j = 0; j < 8; ++j) v[j] = of[j] + gf[j] * v[j];
;             } else {
; #pragma unroll
;                 for (int j = 0; j < 8; ++j) v[j] = gf[j] * v[j];
;             }
;             *(u32x4*)mp = pack8(v);
;         }
	s_waitcnt lgkmcnt(0)
	v_lshlrev_b32_e32 v184, 16, v144
	v_and_b32_e32 v185, 0xffff0000, v144
	v_lshlrev_b32_e32 v186, 16, v176
	v_and_b32_e32 v187, 0xffff0000, v176
	v_pk_fma_f32 v[244:245], v[244:245], v[184:185], v[186:187]
	v_lshlrev_b32_e32 v184, 16, v145
	v_and_b32_e32 v185, 0xffff0000, v145
	v_lshlrev_b32_e32 v186, 16, v177
	v_and_b32_e32 v187, 0xffff0000, v177
	v_pk_fma_f32 v[246:247], v[246:247], v[184:185], v[186:187]
	v_lshlrev_b32_e32 v184, 16, v146
	v_and_b32_e32 v185, 0xffff0000, v146
	v_lshlrev_b32_e32 v186, 16, v178
	v_and_b32_e32 v187, 0xffff0000, v178
	v_pk_fma_f32 v[220:221], v[220:221], v[184:185], v[186:187]
	v_lshlrev_b32_e32 v184, 16, v147
	v_and_b32_e32 v185, 0xffff0000, v147
	v_lshlrev_b32_e32 v186, 16, v179
	v_and_b32_e32 v187, 0xffff0000, v179
	v_pk_fma_f32 v[222:223], v[222:223], v[184:185], v[186:187]
	v_cvt_pk_bf16_f32 v144, v244, v245
	v_cvt_pk_bf16_f32 v145, v246, v247
	v_cvt_pk_bf16_f32 v146, v220, v221
	v_cvt_pk_bf16_f32 v147, v222, v223
	v_add_u32_e32 v219, 0x4000, v218
	global_store_dwordx4 v219, v[144:147], s[22:23]
	v_add_u32_e32 v219, 10, v212
	v_and_b32_e32 v219, 7, v219
	v_xor_b32_e32 v219, v213, v219
	v_add_u32_e32 v228, 10, v215
	v_lshlrev_b32_e32 v228, 10, v228
	v_lshl_add_u32 v228, v219, 4, v228
	v_xor_b32_e32 v229, 16, v228
	ds_read_b128 v[244:247], v228
	ds_read_b128 v[220:223], v229
	s_waitcnt vmcnt(9)
	s_waitcnt lgkmcnt(0)
	v_lshlrev_b32_e32 v184, 16, v148
	v_and_b32_e32 v185, 0xffff0000, v148
	v_lshlrev_b32_e32 v186, 16, v180
	v_and_b32_e32 v187, 0xffff0000, v180
	v_pk_fma_f32 v[244:245], v[244:245], v[184:185], v[186:187]
	v_lshlrev_b32_e32 v184, 16, v149
	v_and_b32_e32 v185, 0xffff0000, v149
	v_lshlrev_b32_e32 v186, 16, v181
	v_and_b32_e32 v187, 0xffff0000, v181
	v_pk_fma_f32 v[246:247], v[246:247], v[184:185], v[186:187]
	v_lshlrev_b32_e32 v184, 16, v150
	v_and_b32_e32 v185, 0xffff0000, v150
	v_lshlrev_b32_e32 v186, 16, v182
	v_and_b32_e32 v187, 0xffff0000, v182
	v_pk_fma_f32 v[220:221], v[220:221], v[184:185], v[186:187]
	v_lshlrev_b32_e32 v184, 16, v151
	v_and_b32_e32 v185, 0xffff0000, v151
	v_lshlrev_b32_e32 v186, 16, v183
	v_and_b32_e32 v187, 0xffff0000, v183
	v_pk_fma_f32 v[222:223], v[222:223], v[184:185], v[186:187]
	v_cvt_pk_bf16_f32 v148, v244, v245
	v_cvt_pk_bf16_f32 v149, v246, v247
	v_cvt_pk_bf16_f32 v150, v220, v221
	v_cvt_pk_bf16_f32 v151, v222, v223
	v_add_u32_e32 v219, 0x5000, v218
	global_store_dwordx4 v219, v[148:151], s[22:23]
	v_add_u32_e32 v219, 12, v212
	v_and_b32_e32 v219, 7, v219
	v_xor_b32_e32 v219, v213, v219
	v_add_u32_e32 v228, 12, v215
	v_lshlrev_b32_e32 v228, 10, v228
	v_lshl_add_u32 v228, v219, 4, v228
	v_xor_b32_e32 v229, 16, v228
	ds_read_b128 v[244:247], v228
	ds_read_b128 v[220:223], v229
	s_waitcnt vmcnt(8)
	s_waitcnt lgkmcnt(0)
	v_lshlrev_b32_e32 v184, 16, v152
	v_and_b32_e32 v185, 0xffff0000, v152
	v_lshlrev_b32_e32 v186, 16, v224
	v_and_b32_e32 v187, 0xffff0000, v224
	v_pk_fma_f32 v[244:245], v[244:245], v[184:185], v[186:187]
	v_lshlrev_b32_e32 v184, 16, v153
	v_and_b32_e32 v185, 0xffff0000, v153
	v_lshlrev_b32_e32 v186, 16, v225
	v_and_b32_e32 v187, 0xffff0000, v225
	v_pk_fma_f32 v[246:247], v[246:247], v[184:185], v[186:187]
	v_lshlrev_b32_e32 v184, 16, v154
	v_and_b32_e32 v185, 0xffff0000, v154
	v_lshlrev_b32_e32 v186, 16, v226
	v_and_b32_e32 v187, 0xffff0000, v226
	v_pk_fma_f32 v[220:221], v[220:221], v[184:185], v[186:187]
	v_lshlrev_b32_e32 v184, 16, v155
	v_and_b32_e32 v185, 0xffff0000, v155
	v_lshlrev_b32_e32 v186, 16, v227
	v_and_b32_e32 v187, 0xffff0000, v227
	v_pk_fma_f32 v[222:223], v[222:223], v[184:185], v[186:187]
	v_cvt_pk_bf16_f32 v152, v244, v245
	v_cvt_pk_bf16_f32 v153, v246, v247
	v_cvt_pk_bf16_f32 v154, v220, v221
	v_cvt_pk_bf16_f32 v155, v222, v223
	v_add_u32_e32 v219, 0x6000, v218
	global_store_dwordx4 v219, v[152:155], s[22:23]
	v_add_u32_e32 v219, 14, v212
	v_and_b32_e32 v219, 7, v219
	v_xor_b32_e32 v219, v213, v219
	v_add_u32_e32 v228, 14, v215
	v_lshlrev_b32_e32 v228, 10, v228
	v_lshl_add_u32 v228, v219, 4, v228
	v_xor_b32_e32 v229, 16, v228
	ds_read_b128 v[244:247], v228
	ds_read_b128 v[220:223], v229
	s_waitcnt vmcnt(7)
	s_waitcnt lgkmcnt(0)
	v_lshlrev_b32_e32 v184, 16, v156
	v_and_b32_e32 v185, 0xffff0000, v156
	v_lshlrev_b32_e32 v186, 16, v240
	v_and_b32_e32 v187, 0xffff0000, v240
	v_pk_fma_f32 v[244:245], v[244:245], v[184:185], v[186:187]
	v_lshlrev_b32_e32 v184, 16, v157
	v_and_b32_e32 v185, 0xffff0000, v157
	v_lshlrev_b32_e32 v186, 16, v241
	v_and_b32_e32 v187, 0xffff0000, v241
	v_pk_fma_f32 v[246:247], v[246:247], v[184:185], v[186:187]
	v_lshlrev_b32_e32 v184, 16, v158
	v_and_b32_e32 v185, 0xffff0000, v158
	v_lshlrev_b32_e32 v186, 16, v242
	v_and_b32_e32 v187, 0xffff0000, v242
	v_pk_fma_f32 v[220:221], v[220:221], v[184:185], v[186:187]
	v_lshlrev_b32_e32 v184, 16, v159
	v_and_b32_e32 v185, 0xffff0000, v159
	v_lshlrev_b32_e32 v186, 16, v243
	v_and_b32_e32 v187, 0xffff0000, v243
	v_pk_fma_f32 v[222:223], v[222:223], v[184:185], v[186:187]
	v_cvt_pk_bf16_f32 v156, v244, v245
	v_cvt_pk_bf16_f32 v157, v246, v247
	v_cvt_pk_bf16_f32 v158, v220, v221
	v_cvt_pk_bf16_f32 v159, v222, v223
	v_add_u32_e32 v219, 0x7000, v218
	global_store_dwordx4 v219, v[156:159], s[22:23]
	s_mov_b32 s61, 0xc000
	s_mov_b32 s60, 0x39800000
	s_mov_b64 s[8:9], 0x1000
	s_mov_b64 s[6:7], -1
	s_andn2_b64 vcc, exec, s[14:15]
	s_cbranch_vccnz .LBB0_1211
	s_andn2_b64 vcc, exec, s[16:17]
	s_cbranch_vccnz .LBB0_1210
	s_barrier
	s_branch .LBB0_1210

; #define EPI_FOR(u) \
;     _Pragma("unroll") for (int ai = 0; ai < 2; ++ai) _Pragma("unroll") for (int m = 0; m < 4; ++m) _Pragma("unroll") for (int bj = 0; bj < 2; ++bj)
; #define EPI_COL(u) (EPI_CB(u) + 8 * fq)
; DI u32x4 pack8(const float* v) { u32x4 w; w.x = pk2(v[0], v[1]); w.y = pk2(v[2], v[3]); w.z = pk2(v[4], v[5]); w.w = pk2(v[6], v[7]); return w; }
;     DI void operator()(const Acc& acc, const Unit& u, int wr, int wc, int fr, int fq) const {
;         EPI_FOR(u) {
;             const int row = EPI_ROW(u), col = EPI_COL(u); EPI_V(v);
;             const u32x4 gg = *(const u32x4*)(gate + (size_t)row * 3072 + gi * 1024 + col);
;             const float gf[8] = {bflo(gg.x), bfhi(gg.x), bflo(gg.y), bfhi(gg.y), bflo(gg.z), bfhi(gg.z), bflo(gg.w), bfhi(gg.w)};
;             bf16_t* mp = mrg + (size_t)row * 1024 + col;
;             if (accum) {
;                 const u32x4 oo = *(const u32x4*)mp;
;                 const float of[8] = {bflo(oo.x), bfhi(oo.x), bflo(oo.y), bfhi(oo.y), bflo(oo.z), bfhi(oo.z), bflo(oo.w), bfhi(oo.w)};
; #pragma unroll
;                 for (int j = 0; j < 8; ++j) v[j] = of[j] + gf[j] * v[j];
;             } else {
; #pragma unroll
;                 for (int j = 0; j < 8; ++j) v[j] = gf[j] * v[j];
;             }
;             *(u32x4*)mp = pack8(v);
;         }
.LBB0_1248:
	s_lshl_b32 s2, s28, 8
	s_lshl_b32 s6, s29, 8
	v_readfirstlane_b32 s7, v232
	s_lshr_b32 s7, s7, 6
	s_lshl_b32 s7, s7, 4
	v_add_u32_e32 v210, s51, v145
	v_lshlrev_b32_e32 v210, 10, v210
	v_and_b32_e32 v211, 7, v145
	v_lshlrev_b32_e32 v212, 1, v144
	v_xor_b32_e32 v211, v212, v211
	v_lshl_add_u32 v210, v211, 4, v210
	s_lshl_b32 s8, s54, 2
	v_add_u32_e32 v210, s8, v210
	v_xor_b32_e32 v211, 16, v210
	v_lshrrev_b32_e32 v212, 5, v233
	v_and_b32_e32 v213, 31, v233
	v_lshl_add_u32 v214, v213, 3, s6
	v_lshlrev_b32_e32 v214, 1, v214
	v_lshlrev_b32_e32 v213, 1, v213

; #define EPI_FOR(u) \
;     _Pragma("unroll") for (int ai = 0; ai < 2; ++ai) _Pragma("unroll") for (int m = 0; m < 4; ++m) _Pragma("unroll") for (int bj = 0; bj < 2; ++bj)
; #define EPI_COL(u) (EPI_CB(u) + 8 * fq)
; DI u32x4 pack8(const float* v) { u32x4 w; w.x = pk2(v[0], v[1]); w.y = pk2(v[2], v[3]); w.z = pk2(v[4], v[5]); w.w = pk2(v[6], v[7]); return w; }
;     DI void operator()(const Acc& acc, const Unit& u, int wr, int wc, int fr, int fq) const {
;         EPI_FOR(u) {
;             const int row = EPI_ROW(u), col = EPI_COL(u); EPI_V(v);
;             const u32x4 gg = *(const u32x4*)(gate + (size_t)row * 3072 + gi * 1024 + col);
;             const float gf[8] = {bflo(gg.x), bfhi(gg.x), bflo(gg.y), bfhi(gg.y), bflo(gg.z), bfhi(gg.z), bflo(gg.w), bfhi(gg.w)};
;             bf16_t* mp = mrg + (size_t)row * 1024 + col;
;             if (accum) {
;                 const u32x4 oo = *(const u32x4*)mp;
;                 const float of[8] = {bflo(oo.x), bfhi(oo.x), bflo(oo.y), bfhi(oo.y), bflo(oo.z), bfhi(oo.z), bflo(oo.w), bfhi(oo.w)};
; #pragma unroll
;                 for (int j = 0; j < 8; ++j) v[j] = of[j] + gf[j] * v[j];
;             } else {
; #pragma unroll
;                 for (int j = 0; j < 8; ++j) v[j] = gf[j] * v[j];
;             }
;             *(u32x4*)mp = pack8(v);
;         }
	v_add_u32_e32 v215, s7, v212
	s_add_i32 s8, s2, 0
	v_add_u32_e32 v216, s8, v215
	v_mul_u32_u24_e32 v217, 0x1800, v216
	v_add_u32_e32 v217, v217, v214
	v_add_u32_e32 v217, 0x800, v217
	v_lshl_add_u32 v218, v216, 11, v214
	global_load_dwordx4 v[128:131], v217, s[22:23]
	global_load_dwordx4 v[160:163], v218, s[24:25]
	v_add_u32_e32 v219, 0x3000, v217
	global_load_dwordx4 v[132:135], v219, s[22:23]
	v_add_u32_e32 v219, 0x1000, v218
	global_load_dwordx4 v[164:167], v219, s[24:25]
	v_add_u32_e32 v219, 0x6000, v217
	global_load_dwordx4 v[136:139], v219, s[22:23]
	v_add_u32_e32 v219, 0x2000, v218
	global_load_dwordx4 v[168:171], v219, s[24:25]
	v_add_u32_e32 v219, 0x9000, v217
	global_load_dwordx4 v[140:143], v219, s[22:23]
	v_add_u32_e32 v219, 0x3000, v218
	global_load_dwordx4 v[172:175], v219, s[24:25]
	v_add_u32_e32 v219, 0xc000, v217
	global_load_dwordx4 v[144:147], v219, s[22:23]
	v_add_u32_e32 v219, 0x4000, v218
	global_load_dwordx4 v[176:179], v219, s[24:25]
	v_add_u32_e32 v219, 0xf000, v217
	global_load_dwordx4 v[148:151], v219, s[22:23]
	v_add_u32_e32 v219, 0x5000, v218
	global_load_dwordx4 v[180:183], v219, s[24:25]
	v_add_u32_e32 v219, 0x12000, v217
	global_load_dwordx4 v[152:155], v219, s[22:23]
	v_add_u32_e32 v219, 0x6000, v218
	global_load_dwordx4 v[224:227], v219, s[24:25]
	v_add_u32_e32 v219, 0x15000, v217
	global_load_dwordx4 v[156:159], v219, s[22:23]
	v_add_u32_e32 v219, 0x7000, v218
	global_load_dwordx4 v[240:243], v219, s[24:25]
	s_waitcnt vmcnt(16)
	s_barrier
	ds_write_b128 v210, v[124:127]
	ds_write_b128 v211, v[120:123]
	ds_write_b128 v210, v[116:119] offset:512
	ds_write_b128 v211, v[112:115] offset:512
	ds_write_b128 v210, v[108:111] offset:16384
	ds_write_b128 v211, v[104:107] offset:16384
	ds_write_b128 v210, v[100:103] offset:16896
	ds_write_b128 v211, v[96:99] offset:16896
	ds_write_b128 v210, v[92:95] offset:32768
	ds_write_b128 v211, v[88:91] offset:32768
	ds_write_b128 v210, v[84:87] offset:33280
	ds_write_b128 v211, v[80:83] offset:33280
	ds_write_b128 v210, v[76:79] offset:49152
	ds_write_b128 v211, v[72:75] offset:49152
	ds_write_b128 v210, v[68:71] offset:49664
	ds_write_b128 v211, v[64:67] offset:49664
	s_waitcnt lgkmcnt(0)
	s_barrier
	v_add_u32_e32 v219, 0, v212
	v_and_b32_e32 v219, 7, v219
	v_xor_b32_e32 v219, v213, v219
	v_add_u32_e32 v228, 0, v215
	v_lshlrev_b32_e32 v228, 10, v228
	v_lshl_add_u32 v228, v219, 4, v228
	v_xor_b32_e32 v229, 16, v228
	ds_read_b128 v[244:247], v228
	ds_read_b128 v[220:223], v229
	s_waitcnt vmcnt(14)
	s_waitcnt lgkmcnt(0)
	v_lshlrev_b32_e32 v184, 16, v128
	v_and_b32_e32 v185, 0xffff0000, v128
	v_lshlrev_b32_e32 v186, 16, v160
	v_and_b32_e32 v187, 0xffff0000, v160
	v_pk_fma_f32 v[244:245], v[244:245], v[184:185], v[186:187]
	v_lshlrev_b32_e32 v184, 16, v129
	v_and_b32_e32 v185, 0xffff0000, v129
	v_lshlrev_b32_e32 v186, 16, v161
	v_and_b32_e32 v187, 0xffff0000, v161
	v_pk_fma_f32 v[246:247], v[246:247], v[184:185], v[186:187]
	v_lshlrev_b32_e32 v184, 16, v130
	v_and_b32_e32 v185, 0xffff0000, v130
	v_lshlrev_b32_e32 v186, 16, v162
	v_and_b32_e32 v187, 0xffff0000, v162
	v_pk_fma_f32 v[220:221], v[220:221], v[184:185], v[186:187]
	v_lshlrev_b32_e32 v184, 16, v131
	v_and_b32_e32 v185, 0xffff0000, v131
	v_lshlrev_b32_e32 v186, 16, v163
	v_and_b32_e32 v187, 0xffff0000, v163
	v_pk_fma_f32 v[222:223], v[222:223], v[184:185], v[186:187]
	v_cvt_pk_bf16_f32 v128, v244, v245
	v_cvt_pk_bf16_f32 v129, v246, v247
	v_cvt_pk_bf16_f32 v130, v220, v221
	v_cvt_pk_bf16_f32 v131, v222, v223
	global_store_dwordx4 v218, v[128:131], s[24:25]
	v_add_u32_e32 v219, 2, v212
	v_and_b32_e32 v219, 7, v219
	v_xor_b32_e32 v219, v213, v219
	v_add_u32_e32 v228, 2, v215
	v_lshlrev_b32_e32 v228, 10, v228
	v_lshl_add_u32 v228, v219, 4, v228
	v_xor_b32_e32 v229, 16, v228
	ds_read_b128 v[244:247], v228
	ds_read_b128 v[220:223], v229
	s_waitcnt vmcnt(13)
	s_waitcnt lgkmcnt(0)
	v_lshlrev_b32_e32 v184, 16, v132
	v_and_b32_e32 v185, 0xffff0000, v132
	v_lshlrev_b32_e32 v186, 16, v164
	v_and_b32_e32 v187, 0xffff0000, v164
	v_pk_fma_f32 v[244:245], v[244:245], v[184:185], v[186:187]
	v_lshlrev_b32_e32 v184, 16, v133
	v_and_b32_e32 v185, 0xffff0000, v133
	v_lshlrev_b32_e32 v186, 16, v165
	v_and_b32_e32 v187, 0xffff0000, v165
	v_pk_fma_f32 v[246:247], v[246:247], v[184:185], v[186:187]
	v_lshlrev_b32_e32 v184, 16, v134
	v_and_b32_e32 v185, 0xffff0000, v134
	v_lshlrev_b32_e32 v186, 16, v166
	v_and_b32_e32 v187, 0xffff0000, v166
	v_pk_fma_f32 v[220:221], v[220:221], v[184:185], v[186:187]
	v_lshlrev_b32_e32 v184, 16, v135
	v_and_b32_e32 v185, 0xffff0000, v135
	v_lshlrev_b32_e32 v186, 16, v167
	v_and_b32_e32 v187, 0xffff0000, v167
	v_pk_fma_f32 v[222:223], v[222:223], v[184:185], v[186:187]
	v_cvt_pk_bf16_f32 v132, v244, v245
	v_cvt_pk_bf16_f32 v133, v246, v247
	v_cvt_pk_bf16_f32 v134, v220, v221
	v_cvt_pk_bf16_f32 v135, v222, v223
	v_add_u32_e32 v219, 0x1000, v218
	global_store_dwordx4 v219, v[132:135], s[24:25]
	v_add_u32_e32 v219, 4, v212
	v_and_b32_e32 v219, 7, v219
	v_xor_b32_e32 v219, v213, v219
	v_add_u32_e32 v228, 4, v215
	v_lshlrev_b32_e32 v228, 10, v228
	v_lshl_add_u32 v228, v219, 4, v228
	v_xor_b32_e32 v229, 16, v228
	ds_read_b128 v[244:247], v228
	ds_read_b128 v[220:223], v229
	s_waitcnt vmcnt(12)
	s_waitcnt lgkmcnt(0)
; #define EPI_FOR(u) \
;     _Pragma("unroll") for (int ai = 0; ai < 2; ++ai) _Pragma("unroll") for (int m = 0; m < 4; ++m) _Pragma("unroll") for (int bj = 0; bj < 2; ++bj)
; #define EPI_COL(u) (EPI_CB(u) + 8 * fq)
; DI u32x4 pack8(const float* v) { u32x4 w; w.x = pk2(v[0], v[1]); w.y = pk2(v[2], v[3]); w.z = pk2(v[4], v[5]); w.w = pk2(v[6], v[7]); return w; }
;     DI void operator()(const Acc& acc, const Unit& u, int wr, int wc, int fr, int fq) const {
;         EPI_FOR(u) {
;             const int row = EPI_ROW(u), col = EPI_COL(u); EPI_V(v);
;             const u32x4 gg = *(const u32x4*)(gate + (size_t)row * 3072 + gi * 1024 + col);
;             const float gf[8] = {bflo(gg.x), bfhi(gg.x), bflo(gg.y), bfhi(gg.y), bflo(gg.z), bfhi(gg.z), bflo(gg.w), bfhi(gg.w)};
;             bf16_t* mp = mrg + (size_t)row * 1024 + col;
;             if (accum) {
;                 const u32x4 oo = *(const u32x4*)mp;
;                 const float of[8] = {bflo(oo.x), bfhi(oo.x), bflo(oo.y), bfhi(oo.y), bflo(oo.z), bfhi(oo.z), bflo(oo.w), bfhi(oo.w)};
; #pragma unroll
;                 for (int j = 0; j < 8; ++j) v[j] = of[j] + gf[j] * v[j];
;             } else {
; #pragma unroll
;                 for (int j = 0; j < 8; ++j) v[j] = gf[j] * v[j];
;             }
;             *(u32x4*)mp = pack8(v);
;         }
	v_lshlrev_b32_e32 v184, 16, v136
	v_and_b32_e32 v185, 0xffff0000, v136
	v_lshlrev_b32_e32 v186, 16, v168
	v_and_b32_e32 v187, 0xffff0000, v168
	v_pk_fma_f32 v[244:245], v[244:245], v[184:185], v[186:187]
	v_lshlrev_b32_e32 v184, 16, v137
	v_and_b32_e32 v185, 0xffff0000, v137
	v_lshlrev_b32_e32 v186, 16, v169
	v_and_b32_e32 v187, 0xffff0000, v169
	v_pk_fma_f32 v[246:247], v[246:247], v[184:185], v[186:187]
	v_lshlrev_b32_e32 v184, 16, v138
	v_and_b32_e32 v185, 0xffff0000, v138
	v_lshlrev_b32_e32 v186, 16, v170
	v_and_b32_e32 v187, 0xffff0000, v170
	v_pk_fma_f32 v[220:221], v[220:221], v[184:185], v[186:187]
	v_lshlrev_b32_e32 v184, 16, v139
	v_and_b32_e32 v185, 0xffff0000, v139
	v_lshlrev_b32_e32 v186, 16, v171
	v_and_b32_e32 v187, 0xffff0000, v171
	v_pk_fma_f32 v[222:223], v[222:223], v[184:185], v[186:187]
	v_cvt_pk_bf16_f32 v136, v244, v245
	v_cvt_pk_bf16_f32 v137, v246, v247
	v_cvt_pk_bf16_f32 v138, v220, v221
	v_cvt_pk_bf16_f32 v139, v222, v223
	v_add_u32_e32 v219, 0x2000, v218
	global_store_dwordx4 v219, v[136:139], s[24:25]
	v_add_u32_e32 v219, 6, v212
	v_and_b32_e32 v219, 7, v219
	v_xor_b32_e32 v219, v213, v219
	v_add_u32_e32 v228, 6, v215
	v_lshlrev_b32_e32 v228, 10, v228
	v_lshl_add_u32 v228, v219, 4, v228
	v_xor_b32_e32 v229, 16, v228
	ds_read_b128 v[244:247], v228
	ds_read_b128 v[220:223], v229
	s_waitcnt vmcnt(11)
	s_waitcnt lgkmcnt(0)
	v_lshlrev_b32_e32 v184, 16, v140
	v_and_b32_e32 v185, 0xffff0000, v140
	v_lshlrev_b32_e32 v186, 16, v172
	v_and_b32_e32 v187, 0xffff0000, v172
	v_pk_fma_f32 v[244:245], v[244:245], v[184:185], v[186:187]
	v_lshlrev_b32_e32 v184, 16, v141
	v_and_b32_e32 v185, 0xffff0000, v141
	v_lshlrev_b32_e32 v186, 16, v173
	v_and_b32_e32 v187, 0xffff0000, v173
	v_pk_fma_f32 v[246:247], v[246:247], v[184:185], v[186:187]
	v_lshlrev_b32_e32 v184, 16, v142
	v_and_b32_e32 v185, 0xffff0000, v142
	v_lshlrev_b32_e32 v186, 16, v174
	v_and_b32_e32 v187, 0xffff0000, v174
	v_pk_fma_f32 v[220:221], v[220:221], v[184:185], v[186:187]
	v_lshlrev_b32_e32 v184, 16, v143
	v_and_b32_e32 v185, 0xffff0000, v143
	v_lshlrev_b32_e32 v186, 16, v175
	v_and_b32_e32 v187, 0xffff0000, v175
	v_pk_fma_f32 v[222:223], v[222:223], v[184:185], v[186:187]
	v_cvt_pk_bf16_f32 v140, v244, v245
	v_cvt_pk_bf16_f32 v141, v246, v247
	v_cvt_pk_bf16_f32 v142, v220, v221
	v_cvt_pk_bf16_f32 v143, v222, v223
	v_add_u32_e32 v219, 0x3000, v218
	global_store_dwordx4 v219, v[140:143], s[24:25]
	v_add_u32_e32 v219, 8, v212
	v_and_b32_e32 v219, 7, v219
	v_xor_b32_e32 v219, v213, v219
	v_add_u32_e32 v228, 8, v215
	v_lshlrev_b32_e32 v228, 10, v228
	v_lshl_add_u32 v228, v219, 4, v228
	v_xor_b32_e32 v229, 16, v228
	ds_read_b128 v[244:247], v228
	ds_read_b128 v[220:223], v229
	s_waitcnt vmcnt(10)
	s_waitcnt lgkmcnt(0)
	v_lshlrev_b32_e32 v184, 16, v144
	v_and_b32_e32 v185, 0xffff0000, v144
	v_lshlrev_b32_e32 v186, 16, v176
	v_and_b32_e32 v187, 0xffff0000, v176
	v_pk_fma_f32 v[244:245], v[244:245], v[184:185], v[186:187]
	v_lshlrev_b32_e32 v184, 16, v145
	v_and_b32_e32 v185, 0xffff0000, v145
	v_lshlrev_b32_e32 v186, 16, v177
	v_and_b32_e32 v187, 0xffff0000, v177
	v_pk_fma_f32 v[246:247], v[246:247], v[184:185], v[186:187]
	v_lshlrev_b32_e32 v184, 16, v146
	v_and_b32_e32 v185, 0xffff0000, v146
	v_lshlrev_b32_e32 v186, 16, v178
	v_and_b32_e32 v187, 0xffff0000, v178
	v_pk_fma_f32 v[220:221], v[220:221], v[184:185], v[186:187]
	v_lshlrev_b32_e32 v184, 16, v147
	v_and_b32_e32 v185, 0xffff0000, v147
	v_lshlrev_b32_e32 v186, 16, v179
	v_and_b32_e32 v187, 0xffff0000, v179
	v_pk_fma_f32 v[222:223], v[222:223], v[184:185], v[186:187]
	v_cvt_pk_bf16_f32 v144, v244, v245
	v_cvt_pk_bf16_f32 v145, v246, v247
	v_cvt_pk_bf16_f32 v146, v220, v221
	v_cvt_pk_bf16_f32 v147, v222, v223
	v_add_u32_e32 v219, 0x4000, v218
	global_store_dwordx4 v219, v[144:147], s[24:25]
	v_add_u32_e32 v219, 10, v212
	v_and_b32_e32 v219, 7, v219
	v_xor_b32_e32 v219, v213, v219
	v_add_u32_e32 v228, 10, v215
	v_lshlrev_b32_e32 v228, 10, v228
	v_lshl_add_u32 v228, v219, 4, v228
	v_xor_b32_e32 v229, 16, v228
	ds_read_b128 v[244:247], v228
	ds_read_b128 v[220:223], v229
	s_waitcnt vmcnt(9)
	s_waitcnt lgkmcnt(0)
	v_lshlrev_b32_e32 v184, 16, v148
	v_and_b32_e32 v185, 0xffff0000, v148
	v_lshlrev_b32_e32 v186, 16, v180
	v_and_b32_e32 v187, 0xffff0000, v180
	v_pk_fma_f32 v[244:245], v[244:245], v[184:185], v[186:187]
	v_lshlrev_b32_e32 v184, 16, v149
	v_and_b32_e32 v185, 0xffff0000, v149
	v_lshlrev_b32_e32 v186, 16, v181
	v_and_b32_e32 v187, 0xffff0000, v181
	v_pk_fma_f32 v[246:247], v[246:247], v[184:185], v[186:187]
	v_lshlrev_b32_e32 v184, 16, v150
	v_and_b32_e32 v185, 0xffff0000, v150
	v_lshlrev_b32_e32 v186, 16, v182
	v_and_b32_e32 v187, 0xffff0000, v182
	v_pk_fma_f32 v[220:221], v[220:221], v[184:185], v[186:187]
	v_lshlrev_b32_e32 v184, 16, v151
	v_and_b32_e32 v185, 0xffff0000, v151
	v_lshlrev_b32_e32 v186, 16, v183
	v_and_b32_e32 v187, 0xffff0000, v183
	v_pk_fma_f32 v[222:223], v[222:223], v[184:185], v[186:187]
	v_cvt_pk_bf16_f32 v148, v244, v245
	v_cvt_pk_bf16_f32 v149, v246, v247
	v_cvt_pk_bf16_f32 v150, v220, v221
	v_cvt_pk_bf16_f32 v151, v222, v223
	v_add_u32_e32 v219, 0x5000, v218
	global_store_dwordx4 v219, v[148:151], s[24:25]
	v_add_u32_e32 v219, 12, v212
	v_and_b32_e32 v219, 7, v219
	v_xor_b32_e32 v219, v213, v219
	v_add_u32_e32 v228, 12, v215
	v_lshlrev_b32_e32 v228, 10, v228
	v_lshl_add_u32 v228, v219, 4, v228
	v_xor_b32_e32 v229, 16, v228
	ds_read_b128 v[244:247], v228
	ds_read_b128 v[220:223], v229
	s_waitcnt vmcnt(8)
	s_waitcnt lgkmcnt(0)
; #define EPI_FOR(u) \
;     _Pragma("unroll") for (int ai = 0; ai < 2; ++ai) _Pragma("unroll") for (int m = 0; m < 4; ++m) _Pragma("unroll") for (int bj = 0; bj < 2; ++bj)
; #define EPI_COL(u) (EPI_CB(u) + 8 * fq)
; DI u32x4 pack8(const float* v) { u32x4 w; w.x = pk2(v[0], v[1]); w.y = pk2(v[2], v[3]); w.z = pk2(v[4], v[5]); w.w = pk2(v[6], v[7]); return w; }
;     DI void operator()(const Acc& acc, const Unit& u, int wr, int wc, int fr, int fq) const {
;         EPI_FOR(u) {
;             const int row = EPI_ROW(u), col = EPI_COL(u); EPI_V(v);
;             const u32x4 gg = *(const u32x4*)(gate + (size_t)row * 3072 + gi * 1024 + col);
;             const float gf[8] = {bflo(gg.x), bfhi(gg.x), bflo(gg.y), bfhi(gg.y), bflo(gg.z), bfhi(gg.z), bflo(gg.w), bfhi(gg.w)};
;             bf16_t* mp = mrg + (size_t)row * 1024 + col;
;             if (accum) {
;                 const u32x4 oo = *(const u32x4*)mp;
;                 const float of[8] = {bflo(oo.x), bfhi(oo.x), bflo(oo.y), bfhi(oo.y), bflo(oo.z), bfhi(oo.z), bflo(oo.w), bfhi(oo.w)};
; #pragma unroll
;                 for (int j = 0; j < 8; ++j) v[j] = of[j] + gf[j] * v[j];
;             } else {
; #pragma unroll
;                 for (int j = 0; j < 8; ++j) v[j] = gf[j] * v[j];
;             }
;             *(u32x4*)mp = pack8(v);
;         }
	v_lshlrev_b32_e32 v184, 16, v152
	v_and_b32_e32 v185, 0xffff0000, v152
	v_lshlrev_b32_e32 v186, 16, v224
	v_and_b32_e32 v187, 0xffff0000, v224
	v_pk_fma_f32 v[244:245], v[244:245], v[184:185], v[186:187]
	v_lshlrev_b32_e32 v184, 16, v153
	v_and_b32_e32 v185, 0xffff0000, v153
	v_lshlrev_b32_e32 v186, 16, v225
	v_and_b32_e32 v187, 0xffff0000, v225
	v_pk_fma_f32 v[246:247], v[246:247], v[184:185], v[186:187]
	v_lshlrev_b32_e32 v184, 16, v154
	v_and_b32_e32 v185, 0xffff0000, v154
	v_lshlrev_b32_e32 v186, 16, v226
	v_and_b32_e32 v187, 0xffff0000, v226
	v_pk_fma_f32 v[220:221], v[220:221], v[184:185], v[186:187]
	v_lshlrev_b32_e32 v184, 16, v155
	v_and_b32_e32 v185, 0xffff0000, v155
	v_lshlrev_b32_e32 v186, 16, v227
	v_and_b32_e32 v187, 0xffff0000, v227
	v_pk_fma_f32 v[222:223], v[222:223], v[184:185], v[186:187]
	v_cvt_pk_bf16_f32 v152, v244, v245
	v_cvt_pk_bf16_f32 v153, v246, v247
	v_cvt_pk_bf16_f32 v154, v220, v221
	v_cvt_pk_bf16_f32 v155, v222, v223
	v_add_u32_e32 v219, 0x6000, v218
	global_store_dwordx4 v219, v[152:155], s[24:25]
	v_add_u32_e32 v219, 14, v212
	v_and_b32_e32 v219, 7, v219
	v_xor_b32_e32 v219, v213, v219
	v_add_u32_e32 v228, 14, v215
	v_lshlrev_b32_e32 v228, 10, v228
	v_lshl_add_u32 v228, v219, 4, v228
	v_xor_b32_e32 v229, 16, v228
	ds_read_b128 v[244:247], v228
	ds_read_b128 v[220:223], v229
	s_waitcnt vmcnt(7)
	s_waitcnt lgkmcnt(0)
	v_lshlrev_b32_e32 v184, 16, v156
	v_and_b32_e32 v185, 0xffff0000, v156
	v_lshlrev_b32_e32 v186, 16, v240
	v_and_b32_e32 v187, 0xffff0000, v240
	v_pk_fma_f32 v[244:245], v[244:245], v[184:185], v[186:187]
	v_lshlrev_b32_e32 v184, 16, v157
	v_and_b32_e32 v185, 0xffff0000, v157
	v_lshlrev_b32_e32 v186, 16, v241
	v_and_b32_e32 v187, 0xffff0000, v241
	v_pk_fma_f32 v[246:247], v[246:247], v[184:185], v[186:187]
	v_lshlrev_b32_e32 v184, 16, v158
	v_and_b32_e32 v185, 0xffff0000, v158
	v_lshlrev_b32_e32 v186, 16, v242
	v_and_b32_e32 v187, 0xffff0000, v242
	v_pk_fma_f32 v[220:221], v[220:221], v[184:185], v[186:187]
	v_lshlrev_b32_e32 v184, 16, v159
	v_and_b32_e32 v185, 0xffff0000, v159
	v_lshlrev_b32_e32 v186, 16, v243
	v_and_b32_e32 v187, 0xffff0000, v243
	v_pk_fma_f32 v[222:223], v[222:223], v[184:185], v[186:187]
	v_cvt_pk_bf16_f32 v156, v244, v245
	v_cvt_pk_bf16_f32 v157, v246, v247
	v_cvt_pk_bf16_f32 v158, v220, v221
	v_cvt_pk_bf16_f32 v159, v222, v223
	v_add_u32_e32 v219, 0x7000, v218
	global_store_dwordx4 v219, v[156:159], s[24:25]
	v_add_u32_e32 v215, s7, v212
	s_add_i32 s8, s2, 128
	v_add_u32_e32 v216, s8, v215
	v_mul_u32_u24_e32 v217, 0x1800, v216
	v_add_u32_e32 v217, v217, v214
	v_add_u32_e32 v217, 0x800, v217
	v_lshl_add_u32 v218, v216, 11, v214
	global_load_dwordx4 v[128:131], v217, s[22:23]
	global_load_dwordx4 v[160:163], v218, s[24:25]
	v_add_u32_e32 v219, 0x3000, v217
	global_load_dwordx4 v[132:135], v219, s[22:23]
	v_add_u32_e32 v219, 0x1000, v218
	global_load_dwordx4 v[164:167], v219, s[24:25]
	v_add_u32_e32 v219, 0x6000, v217
	global_load_dwordx4 v[136:139], v219, s[22:23]
	v_add_u32_e32 v219, 0x2000, v218
	global_load_dwordx4 v[168:171], v219, s[24:25]
	v_add_u32_e32 v219, 0x9000, v217
	global_load_dwordx4 v[140:143], v219, s[22:23]
	v_add_u32_e32 v219, 0x3000, v218
	global_load_dwordx4 v[172:175], v219, s[24:25]
	v_add_u32_e32 v219, 0xc000, v217
	global_load_dwordx4 v[144:147], v219, s[22:23]
	v_add_u32_e32 v219, 0x4000, v218
	global_load_dwordx4 v[176:179], v219, s[24:25]
	v_add_u32_e32 v219, 0xf000, v217
	global_load_dwordx4 v[148:151], v219, s[22:23]
	v_add_u32_e32 v219, 0x5000, v218
	global_load_dwordx4 v[180:183], v219, s[24:25]
	v_add_u32_e32 v219, 0x12000, v217
	global_load_dwordx4 v[152:155], v219, s[22:23]
	v_add_u32_e32 v219, 0x6000, v218
	global_load_dwordx4 v[224:227], v219, s[24:25]
	v_add_u32_e32 v219, 0x15000, v217
	global_load_dwordx4 v[156:159], v219, s[22:23]
	v_add_u32_e32 v219, 0x7000, v218
	global_load_dwordx4 v[240:243], v219, s[24:25]
	s_barrier
	ds_write_b128 v210, v[60:63]
	ds_write_b128 v211, v[56:59]
	ds_write_b128 v210, v[52:55] offset:512
	ds_write_b128 v211, v[48:51] offset:512
	ds_write_b128 v210, v[44:47] offset:16384
	ds_write_b128 v211, v[40:43] offset:16384
	ds_write_b128 v210, v[36:39] offset:16896
	ds_write_b128 v211, v[32:35] offset:16896
	ds_write_b128 v210, v[28:31] offset:32768
	ds_write_b128 v211, v[24:27] offset:32768
	ds_write_b128 v210, v[20:23] offset:33280
	ds_write_b128 v211, v[16:19] offset:33280
	ds_write_b128 v210, v[12:15] offset:49152
	ds_write_b128 v211, v[8:11] offset:49152
	ds_write_b128 v210, v[4:7] offset:49664
	ds_write_b128 v211, v[0:3] offset:49664
	s_waitcnt lgkmcnt(0)
	s_barrier
; #define EPI_FOR(u) \
;     _Pragma("unroll") for (int ai = 0; ai < 2; ++ai) _Pragma("unroll") for (int m = 0; m < 4; ++m) _Pragma("unroll") for (int bj = 0; bj < 2; ++bj)
; #define EPI_COL(u) (EPI_CB(u) + 8 * fq)
; DI u32x4 pack8(const float* v) { u32x4 w; w.x = pk2(v[0], v[1]); w.y = pk2(v[2], v[3]); w.z = pk2(v[4], v[5]); w.w = pk2(v[6], v[7]); return w; }
;     DI void operator()(const Acc& acc, const Unit& u, int wr, int wc, int fr, int fq) const {
;         EPI_FOR(u) {
;             const int row = EPI_ROW(u), col = EPI_COL(u); EPI_V(v);
;             const u32x4 gg = *(const u32x4*)(gate + (size_t)row * 3072 + gi * 1024 + col);
;             const float gf[8] = {bflo(gg.x), bfhi(gg.x), bflo(gg.y), bfhi(gg.y), bflo(gg.z), bfhi(gg.z), bflo(gg.w), bfhi(gg.w)};
;             bf16_t* mp = mrg + (size_t)row * 1024 + col;
;             if (accum) {
;                 const u32x4 oo = *(const u32x4*)mp;
;                 const float of[8] = {bflo(oo.x), bfhi(oo.x), bflo(oo.y), bfhi(oo.y), bflo(oo.z), bfhi(oo.z), bflo(oo.w), bfhi(oo.w)};
; #pragma unroll
;                 for (int j = 0; j < 8; ++j) v[j] = of[j] + gf[j] * v[j];
;             } else {
; #pragma unroll
;                 for (int j = 0; j < 8; ++j) v[j] = gf[j] * v[j];
;             }
;             *(u32x4*)mp = pack8(v);
;         }
	v_add_u32_e32 v219, 0, v212
	v_and_b32_e32 v219, 7, v219
	v_xor_b32_e32 v219, v213, v219
	v_add_u32_e32 v228, 0, v215
	v_lshlrev_b32_e32 v228, 10, v228
	v_lshl_add_u32 v228, v219, 4, v228
	v_xor_b32_e32 v229, 16, v228
	ds_read_b128 v[244:247], v228
	ds_read_b128 v[220:223], v229
	s_waitcnt vmcnt(14)
	s_waitcnt lgkmcnt(0)
	v_lshlrev_b32_e32 v184, 16, v128
	v_and_b32_e32 v185, 0xffff0000, v128
	v_lshlrev_b32_e32 v186, 16, v160
	v_and_b32_e32 v187, 0xffff0000, v160
	v_pk_fma_f32 v[244:245], v[244:245], v[184:185], v[186:187]
	v_lshlrev_b32_e32 v184, 16, v129
	v_and_b32_e32 v185, 0xffff0000, v129
	v_lshlrev_b32_e32 v186, 16, v161
	v_and_b32_e32 v187, 0xffff0000, v161
	v_pk_fma_f32 v[246:247], v[246:247], v[184:185], v[186:187]
	v_lshlrev_b32_e32 v184, 16, v130
	v_and_b32_e32 v185, 0xffff0000, v130
	v_lshlrev_b32_e32 v186, 16, v162
	v_and_b32_e32 v187, 0xffff0000, v162
	v_pk_fma_f32 v[220:221], v[220:221], v[184:185], v[186:187]
	v_lshlrev_b32_e32 v184, 16, v131
	v_and_b32_e32 v185, 0xffff0000, v131
	v_lshlrev_b32_e32 v186, 16, v163
	v_and_b32_e32 v187, 0xffff0000, v163
	v_pk_fma_f32 v[222:223], v[222:223], v[184:185], v[186:187]
	v_cvt_pk_bf16_f32 v128, v244, v245
	v_cvt_pk_bf16_f32 v129, v246, v247
	v_cvt_pk_bf16_f32 v130, v220, v221
	v_cvt_pk_bf16_f32 v131, v222, v223
	global_store_dwordx4 v218, v[128:131], s[24:25]
	v_add_u32_e32 v219, 2, v212
	v_and_b32_e32 v219, 7, v219
	v_xor_b32_e32 v219, v213, v219
	v_add_u32_e32 v228, 2, v215
	v_lshlrev_b32_e32 v228, 10, v228
	v_lshl_add_u32 v228, v219, 4, v228
	v_xor_b32_e32 v229, 16, v228
	ds_read_b128 v[244:247], v228
	ds_read_b128 v[220:223], v229
	s_waitcnt vmcnt(13)
	s_waitcnt lgkmcnt(0)
	v_lshlrev_b32_e32 v184, 16, v132
	v_and_b32_e32 v185, 0xffff0000, v132
	v_lshlrev_b32_e32 v186, 16, v164
	v_and_b32_e32 v187, 0xffff0000, v164
	v_pk_fma_f32 v[244:245], v[244:245], v[184:185], v[186:187]
	v_lshlrev_b32_e32 v184, 16, v133
	v_and_b32_e32 v185, 0xffff0000, v133
	v_lshlrev_b32_e32 v186, 16, v165
	v_and_b32_e32 v187, 0xffff0000, v165
	v_pk_fma_f32 v[246:247], v[246:247], v[184:185], v[186:187]
	v_lshlrev_b32_e32 v184, 16, v134
	v_and_b32_e32 v185, 0xffff0000, v134
	v_lshlrev_b32_e32 v186, 16, v166
	v_and_b32_e32 v187, 0xffff0000, v166
	v_pk_fma_f32 v[220:221], v[220:221], v[184:185], v[186:187]
	v_lshlrev_b32_e32 v184, 16, v135
	v_and_b32_e32 v185, 0xffff0000, v135
	v_lshlrev_b32_e32 v186, 16, v167
	v_and_b32_e32 v187, 0xffff0000, v167
	v_pk_fma_f32 v[222:223], v[222:223], v[184:185], v[186:187]
	v_cvt_pk_bf16_f32 v132, v244, v245
	v_cvt_pk_bf16_f32 v133, v246, v247
	v_cvt_pk_bf16_f32 v134, v220, v221
	v_cvt_pk_bf16_f32 v135, v222, v223
	v_add_u32_e32 v219, 0x1000, v218
	global_store_dwordx4 v219, v[132:135], s[24:25]
	v_add_u32_e32 v219, 4, v212
	v_and_b32_e32 v219, 7, v219
	v_xor_b32_e32 v219, v213, v219
	v_add_u32_e32 v228, 4, v215
	v_lshlrev_b32_e32 v228, 10, v228
	v_lshl_add_u32 v228, v219, 4, v228
	v_xor_b32_e32 v229, 16, v228
	ds_read_b128 v[244:247], v228
	ds_read_b128 v[220:223], v229
	s_waitcnt vmcnt(12)
	s_waitcnt lgkmcnt(0)
	v_lshlrev_b32_e32 v184, 16, v136
	v_and_b32_e32 v185, 0xffff0000, v136
	v_lshlrev_b32_e32 v186, 16, v168
	v_and_b32_e32 v187, 0xffff0000, v168
	v_pk_fma_f32 v[244:245], v[244:245], v[184:185], v[186:187]
	v_lshlrev_b32_e32 v184, 16, v137
	v_and_b32_e32 v185, 0xffff0000, v137
	v_lshlrev_b32_e32 v186, 16, v169
	v_and_b32_e32 v187, 0xffff0000, v169
	v_pk_fma_f32 v[246:247], v[246:247], v[184:185], v[186:187]
	v_lshlrev_b32_e32 v184, 16, v138
	v_and_b32_e32 v185, 0xffff0000, v138
	v_lshlrev_b32_e32 v186, 16, v170
	v_and_b32_e32 v187, 0xffff0000, v170
	v_pk_fma_f32 v[220:221], v[220:221], v[184:185], v[186:187]
	v_lshlrev_b32_e32 v184, 16, v139
	v_and_b32_e32 v185, 0xffff0000, v139
	v_lshlrev_b32_e32 v186, 16, v171
	v_and_b32_e32 v187, 0xffff0000, v171
	v_pk_fma_f32 v[222:223], v[222:223], v[184:185], v[186:187]
	v_cvt_pk_bf16_f32 v136, v244, v245
	v_cvt_pk_bf16_f32 v137, v246, v247
	v_cvt_pk_bf16_f32 v138, v220, v221
	v_cvt_pk_bf16_f32 v139, v222, v223
	v_add_u32_e32 v219, 0x2000, v218
	global_store_dwordx4 v219, v[136:139], s[24:25]
	v_add_u32_e32 v219, 6, v212
	v_and_b32_e32 v219, 7, v219
	v_xor_b32_e32 v219, v213, v219
	v_add_u32_e32 v228, 6, v215
	v_lshlrev_b32_e32 v228, 10, v228
	v_lshl_add_u32 v228, v219, 4, v228
	v_xor_b32_e32 v229, 16, v228
	ds_read_b128 v[244:247], v228
	ds_read_b128 v[220:223], v229
	s_waitcnt vmcnt(11)
	s_waitcnt lgkmcnt(0)
	v_lshlrev_b32_e32 v184, 16, v140
	v_and_b32_e32 v185, 0xffff0000, v140
	v_lshlrev_b32_e32 v186, 16, v172
	v_and_b32_e32 v187, 0xffff0000, v172
	v_pk_fma_f32 v[244:245], v[244:245], v[184:185], v[186:187]
	v_lshlrev_b32_e32 v184, 16, v141
	v_and_b32_e32 v185, 0xffff0000, v141
	v_lshlrev_b32_e32 v186, 16, v173
	v_and_b32_e32 v187, 0xffff0000, v173
	v_pk_fma_f32 v[246:247], v[246:247], v[184:185], v[186:187]
	v_lshlrev_b32_e32 v184, 16, v142
	v_and_b32_e32 v185, 0xffff0000, v142
	v_lshlrev_b32_e32 v186, 16, v174
	v_and_b32_e32 v187, 0xffff0000, v174
	v_pk_fma_f32 v[220:221], v[220:221], v[184:185], v[186:187]
	v_lshlrev_b32_e32 v184, 16, v143
	v_and_b32_e32 v185, 0xffff0000, v143
	v_lshlrev_b32_e32 v186, 16, v175
	v_and_b32_e32 v187, 0xffff0000, v175
	v_pk_fma_f32 v[222:223], v[222:223], v[184:185], v[186:187]
	v_cvt_pk_bf16_f32 v140, v244, v245
	v_cvt_pk_bf16_f32 v141, v246, v247
	v_cvt_pk_bf16_f32 v142, v220, v221
	v_cvt_pk_bf16_f32 v143, v222, v223
	v_add_u32_e32 v219, 0x3000, v218
	global_store_dwordx4 v219, v[140:143], s[24:25]
	v_add_u32_e32 v219, 8, v212
	v_and_b32_e32 v219, 7, v219
	v_xor_b32_e32 v219, v213, v219
	v_add_u32_e32 v228, 8, v215
	v_lshlrev_b32_e32 v228, 10, v228
	v_lshl_add_u32 v228, v219, 4, v228
	v_xor_b32_e32 v229, 16, v228
	ds_read_b128 v[244:247], v228
	ds_read_b128 v[220:223], v229
	s_waitcnt vmcnt(10)
; #define EPI_FOR(u) \
;     _Pragma("unroll") for (int ai = 0; ai < 2; ++ai) _Pragma("unroll") for (int m = 0; m < 4; ++m) _Pragma("unroll") for (int bj = 0; bj < 2; ++bj)
; #define EPI_COL(u) (EPI_CB(u) + 8 * fq)
; DI u32x4 pack8(const float* v) { u32x4 w; w.x = pk2(v[0], v[1]); w.y = pk2(v[2], v[3]); w.z = pk2(v[4], v[5]); w.w = pk2(v[6], v[7]); return w; }
;     DI void operator()(const Acc& acc, const Unit& u, int wr, int wc, int fr, int fq) const {
;         EPI_FOR(u) {
;             const int row = EPI_ROW(u), col = EPI_COL(u); EPI_V(v);
;             const u32x4 gg = *(const u32x4*)(gate + (size_t)row * 3072 + gi * 1024 + col);
;             const float gf[8] = {bflo(gg.x), bfhi(gg.x), bflo(gg.y), bfhi(gg.y), bflo(gg.z), bfhi(gg.z), bflo(gg.w), bfhi(gg.w)};
;             bf16_t* mp = mrg + (size_t)row * 1024 + col;
;             if (accum) {
;                 const u32x4 oo = *(const u32x4*)mp;
;                 const float of[8] = {bflo(oo.x), bfhi(oo.x), bflo(oo.y), bfhi(oo.y), bflo(oo.z), bfhi(oo.z), bflo(oo.w), bfhi(oo.w)};
; #pragma unroll
;                 for (int j = 0; j < 8; ++j) v[j] = of[j] + gf[j] * v[j];
;             } else {
; #pragma unroll
;                 for (int j = 0; j < 8; ++j) v[j] = gf[j] * v[j];
;             }
;             *(u32x4*)mp = pack8(v);
;         }
	s_waitcnt lgkmcnt(0)
	v_lshlrev_b32_e32 v184, 16, v144
	v_and_b32_e32 v185, 0xffff0000, v144
	v_lshlrev_b32_e32 v186, 16, v176
	v_and_b32_e32 v187, 0xffff0000, v176
	v_pk_fma_f32 v[244:245], v[244:245], v[184:185], v[186:187]
	v_lshlrev_b32_e32 v184, 16, v145
	v_and_b32_e32 v185, 0xffff0000, v145
	v_lshlrev_b32_e32 v186, 16, v177
	v_and_b32_e32 v187, 0xffff0000, v177
	v_pk_fma_f32 v[246:247], v[246:247], v[184:185], v[186:187]
	v_lshlrev_b32_e32 v184, 16, v146
	v_and_b32_e32 v185, 0xffff0000, v146
	v_lshlrev_b32_e32 v186, 16, v178
	v_and_b32_e32 v187, 0xffff0000, v178
	v_pk_fma_f32 v[220:221], v[220:221], v[184:185], v[186:187]
	v_lshlrev_b32_e32 v184, 16, v147
	v_and_b32_e32 v185, 0xffff0000, v147
	v_lshlrev_b32_e32 v186, 16, v179
	v_and_b32_e32 v187, 0xffff0000, v179
	v_pk_fma_f32 v[222:223], v[222:223], v[184:185], v[186:187]
	v_cvt_pk_bf16_f32 v144, v244, v245
	v_cvt_pk_bf16_f32 v145, v246, v247
	v_cvt_pk_bf16_f32 v146, v220, v221
	v_cvt_pk_bf16_f32 v147, v222, v223
	v_add_u32_e32 v219, 0x4000, v218
	global_store_dwordx4 v219, v[144:147], s[24:25]
	v_add_u32_e32 v219, 10, v212
	v_and_b32_e32 v219, 7, v219
	v_xor_b32_e32 v219, v213, v219
	v_add_u32_e32 v228, 10, v215
	v_lshlrev_b32_e32 v228, 10, v228
	v_lshl_add_u32 v228, v219, 4, v228
	v_xor_b32_e32 v229, 16, v228
	ds_read_b128 v[244:247], v228
	ds_read_b128 v[220:223], v229
	s_waitcnt vmcnt(9)
	s_waitcnt lgkmcnt(0)
	v_lshlrev_b32_e32 v184, 16, v148
	v_and_b32_e32 v185, 0xffff0000, v148
	v_lshlrev_b32_e32 v186, 16, v180
	v_and_b32_e32 v187, 0xffff0000, v180
	v_pk_fma_f32 v[244:245], v[244:245], v[184:185], v[186:187]
	v_lshlrev_b32_e32 v184, 16, v149
	v_and_b32_e32 v185, 0xffff0000, v149
	v_lshlrev_b32_e32 v186, 16, v181
	v_and_b32_e32 v187, 0xffff0000, v181
	v_pk_fma_f32 v[246:247], v[246:247], v[184:185], v[186:187]
	v_lshlrev_b32_e32 v184, 16, v150
	v_and_b32_e32 v185, 0xffff0000, v150
	v_lshlrev_b32_e32 v186, 16, v182
	v_and_b32_e32 v187, 0xffff0000, v182
	v_pk_fma_f32 v[220:221], v[220:221], v[184:185], v[186:187]
	v_lshlrev_b32_e32 v184, 16, v151
	v_and_b32_e32 v185, 0xffff0000, v151
	v_lshlrev_b32_e32 v186, 16, v183
	v_and_b32_e32 v187, 0xffff0000, v183
	v_pk_fma_f32 v[222:223], v[222:223], v[184:185], v[186:187]
	v_cvt_pk_bf16_f32 v148, v244, v245
	v_cvt_pk_bf16_f32 v149, v246, v247
	v_cvt_pk_bf16_f32 v150, v220, v221
	v_cvt_pk_bf16_f32 v151, v222, v223
	v_add_u32_e32 v219, 0x5000, v218
	global_store_dwordx4 v219, v[148:151], s[24:25]
	v_add_u32_e32 v219, 12, v212
	v_and_b32_e32 v219, 7, v219
	v_xor_b32_e32 v219, v213, v219
	v_add_u32_e32 v228, 12, v215
	v_lshlrev_b32_e32 v228, 10, v228
	v_lshl_add_u32 v228, v219, 4, v228
	v_xor_b32_e32 v229, 16, v228
	ds_read_b128 v[244:247], v228
	ds_read_b128 v[220:223], v229
	s_waitcnt vmcnt(8)
	s_waitcnt lgkmcnt(0)
	v_lshlrev_b32_e32 v184, 16, v152
	v_and_b32_e32 v185, 0xffff0000, v152
	v_lshlrev_b32_e32 v186, 16, v224
	v_and_b32_e32 v187, 0xffff0000, v224
	v_pk_fma_f32 v[244:245], v[244:245], v[184:185], v[186:187]
	v_lshlrev_b32_e32 v184, 16, v153
	v_and_b32_e32 v185, 0xffff0000, v153
	v_lshlrev_b32_e32 v186, 16, v225
	v_and_b32_e32 v187, 0xffff0000, v225
	v_pk_fma_f32 v[246:247], v[246:247], v[184:185], v[186:187]
	v_lshlrev_b32_e32 v184, 16, v154
	v_and_b32_e32 v185, 0xffff0000, v154
	v_lshlrev_b32_e32 v186, 16, v226
	v_and_b32_e32 v187, 0xffff0000, v226
	v_pk_fma_f32 v[220:221], v[220:221], v[184:185], v[186:187]
	v_lshlrev_b32_e32 v184, 16, v155
	v_and_b32_e32 v185, 0xffff0000, v155
	v_lshlrev_b32_e32 v186, 16, v227
	v_and_b32_e32 v187, 0xffff0000, v227
	v_pk_fma_f32 v[222:223], v[222:223], v[184:185], v[186:187]
	v_cvt_pk_bf16_f32 v152, v244, v245
	v_cvt_pk_bf16_f32 v153, v246, v247
	v_cvt_pk_bf16_f32 v154, v220, v221
	v_cvt_pk_bf16_f32 v155, v222, v223
	v_add_u32_e32 v219, 0x6000, v218
	global_store_dwordx4 v219, v[152:155], s[24:25]
	v_add_u32_e32 v219, 14, v212
	v_and_b32_e32 v219, 7, v219
	v_xor_b32_e32 v219, v213, v219
	v_add_u32_e32 v228, 14, v215
	v_lshlrev_b32_e32 v228, 10, v228
	v_lshl_add_u32 v228, v219, 4, v228
	v_xor_b32_e32 v229, 16, v228
	ds_read_b128 v[244:247], v228
	ds_read_b128 v[220:223], v229
	s_waitcnt vmcnt(7)
	s_waitcnt lgkmcnt(0)
	v_lshlrev_b32_e32 v184, 16, v156
	v_and_b32_e32 v185, 0xffff0000, v156
	v_lshlrev_b32_e32 v186, 16, v240
	v_and_b32_e32 v187, 0xffff0000, v240
	v_pk_fma_f32 v[244:245], v[244:245], v[184:185], v[186:187]
	v_lshlrev_b32_e32 v184, 16, v157
	v_and_b32_e32 v185, 0xffff0000, v157
	v_lshlrev_b32_e32 v186, 16, v241
	v_and_b32_e32 v187, 0xffff0000, v241
	v_pk_fma_f32 v[246:247], v[246:247], v[184:185], v[186:187]
	v_lshlrev_b32_e32 v184, 16, v158
	v_and_b32_e32 v185, 0xffff0000, v158
	v_lshlrev_b32_e32 v186, 16, v242
	v_and_b32_e32 v187, 0xffff0000, v242
	v_pk_fma_f32 v[220:221], v[220:221], v[184:185], v[186:187]
	v_lshlrev_b32_e32 v184, 16, v159
	v_and_b32_e32 v185, 0xffff0000, v159
	v_lshlrev_b32_e32 v186, 16, v243
	v_and_b32_e32 v187, 0xffff0000, v243
	v_pk_fma_f32 v[222:223], v[222:223], v[184:185], v[186:187]
	v_cvt_pk_bf16_f32 v156, v244, v245
	v_cvt_pk_bf16_f32 v157, v246, v247
	v_cvt_pk_bf16_f32 v158, v220, v221
	v_cvt_pk_bf16_f32 v159, v222, v223
	v_add_u32_e32 v219, 0x7000, v218
	global_store_dwordx4 v219, v[156:159], s[24:25]
	s_mov_b64 s[6:7], -1
	s_and_b64 vcc, exec, s[14:15]
	s_cbranch_vccnz .LBB0_1233
	s_andn2_b64 vcc, exec, s[20:21]
	s_cbranch_vccnz .LBB0_1232
	s_barrier
	s_branch .LBB0_1232
